# retention outputs: waves 4-7 start the X/decay/PV interval about 1100 cycles late (one wave's matrix phase beside the other's VALU phase), on the pipelined ladders
# baseline (speedup 1.0000x reference)
; #define RLAS __attribute__((address_space(3)))
; #define LBAR() do { asm volatile("s_waitcnt lgkmcnt(0)" ::: "memory"); __builtin_amdgcn_s_barrier(); asm volatile("" ::: "memory"); } while (0)
; __device__ __forceinline__ void out_unit(RLAS unsigned char* L, int b, int h, int c, const bf16_t* QR, bf16_t* PR, const bf16_t* KR, const bf16_t* VR, const bf16_t* GR, const bf16_t* ST, size_t stbatch, const float* gnw, float lgf, float lgb, OutRegs& PF, bool is_first, bool has_next, int nb, int nh ...
;     ...
;     const size_t tok0 = (size_t)b * SEQ + (size_t)c * 128;
;     const int srow = tid >> 2, sqt = tid & 3;
;     const int grow = (tid >> 6) * 16 + ((tid >> 4) & 3), gch = tid & 15;
;     RLAS unsigned char* R2 = L + REG1 + REGV;
; #pragma unroll
;     for (int i = 0; i < 4; ++i) { *(RLAS u32x4*)(R2 + (grow + 4 * i) * RS + gch * 16) = PF.q[i]; *(RLAS u32x4*)(R0 + (grow + 4 * i) * RS + gch * 16) = PF.k[i]; *(RLAS u32x4*)(R1 + (grow + 4 * i) * RSV + gch * 16) = PF.v[i]; }
;     asm volatile("" ::: "memory"); __builtin_amdgcn_sched_barrier(0);
;     u32x4 sfr[4], sbr[4];
;     { const bf16_t* sf = ST + (size_t)b * stbatch + ((size_t)(0 * 4 + h) * 32 + c) * 16384 + (size_t)grow * 128 + gch * 8;
;       const bf16_t* sb = ST + (size_t)b * stbatch + ((size_t)(1 * 4 + h) * 32 + c) * 16384 + (size_t)grow * 128 + gch * 8;
; #pragma unroll
;       for (int i = 0; i < 4; ++i) { sfr[i] = *(const u32x4*)(sf + (size_t)(4 * i) * 128); sbr[i] = *(const u32x4*)(sb + (size_t)(4 * i) * 128); } }
;     LBAR();
; __global__ void __launch_bounds__(NWAVES * 64, 2) mega_fwd(Args args) {
;     ...
;                 const float lgf = -log2f(1.f + expf(-dec_f[l * 4 + h])), lgb = -log2f(1.f + expf(-dec_b[l * 4 + h]));
.LBB0_502:
	s_bfe_u32 s15, s6, 0x20005
	s_or_b32 s16, s15, s9
	v_readlane_b32 s52, v252, 10
	s_ashr_i32 s0, s6, 7
	s_and_b32 s20, s6, 31
	s_lshl_b64 s[6:7], s[16:17], 2
	v_readlane_b32 s62, v252, 20
	v_readlane_b32 s63, v252, 21
	s_add_u32 s22, s62, s6
	s_addc_u32 s23, s63, s7
	global_load_dword v2, v3, s[22:23]
	s_mov_b32 s5, 0xbfb8aa3b
	s_mov_b32 s16, 0x42ce8ed0
	s_mov_b32 s21, 0xc2b17218
	v_readlane_b32 s64, v252, 22
	v_readlane_b32 s65, v252, 23
	v_mov_b32_e32 v140, v0
	v_readlane_b32 s37, v255, 0
	s_movk_i32 s33, 0x110
	v_readlane_b32 s53, v252, 11
	v_readlane_b32 s54, v252, 12
	v_readlane_b32 s55, v252, 13
	v_readlane_b32 s56, v252, 14
	v_readlane_b32 s57, v252, 15
	v_readlane_b32 s58, v252, 16
	v_readlane_b32 s59, v252, 17
	v_readlane_b32 s60, v252, 18
	v_readlane_b32 s61, v252, 19
	v_readlane_b32 s66, v252, 24
	v_readlane_b32 s67, v252, 25
	s_waitcnt vmcnt(0)
	v_mul_f32_e32 v52, 0xbfb8aa3b, v2
	v_fma_f32 v53, v2, s5, -v52
	v_rndne_f32_e32 v54, v52
	v_fmac_f32_e32 v53, 0xb2a5705f, v2
	v_sub_f32_e32 v52, v52, v54
	v_add_f32_e32 v52, v52, v53
	v_cvt_i32_f32_e32 v54, v54
	v_exp_f32_e32 v52, v52
	v_cmp_nlt_f32_e32 vcc, s16, v2
	v_ldexp_f32 v52, v52, v54
	s_nop 0
	v_cndmask_b32_e32 v52, 0, v52, vcc
	v_cmp_ngt_f32_e32 vcc, s21, v2
	s_nop 1
	v_cndmask_b32_e32 v2, v225, v52, vcc
	v_add_f32_e32 v2, 1.0, v2
	v_cmp_gt_f32_e32 vcc, s35, v2
	s_and_b64 s[22:23], vcc, exec
	s_cselect_b32 s1, 32, 0
	s_add_u32 s6, s64, s6
	s_addc_u32 s7, s65, s7
	global_load_dword v56, v3, s[6:7]
	v_ldexp_f32 v2, v2, s1
	v_log_f32_e32 v54, v2
	v_cndmask_b32_e32 v53, 0, v226, vcc
	v_ashrrev_i32_e32 v2, 6, v140
	v_bfe_u32 v52, v140, 4, 2
	v_and_b32_e32 v148, 15, v140
	v_readfirstlane_b32 s14, v2
	v_lshl_or_b32 v144, v2, 4, v52
	v_lshlrev_b32_e32 v2, 4, v148
	v_add_u32_e32 v57, s37, v2
	v_mul_lo_u32 v58, v144, s33
	v_add_u32_e32 v52, 0, v2
	v_sub_f32_e32 v149, v54, v53
	v_add_u32_e32 v53, v57, v58
	s_movk_i32 s1, 0x140
	v_mad_u64_u32 v[54:55], s[6:7], v144, s1, v[52:53]
	v_add_u32_e32 v55, 0x440, v58
	v_add_u32_e32 v136, v52, v58
	v_add_u32_e32 v59, 0x880, v58
	ds_write_b128 v53, v[16:19]
	ds_write_b128 v136, v[4:7]
	ds_write_b128 v54, v[8:11] offset:34816
	v_add_u32_e32 v4, v57, v55
	v_add_u32_e32 v137, v52, v55
	v_add_u32_e32 v5, v57, v59
	v_add_u32_e32 v138, v52, v59
	ds_write_b128 v4, v[12:15]
	ds_write_b128 v137, v[20:23]
	ds_write_b128 v54, v[28:31] offset:36096
	ds_write_b128 v5, v[40:43]
	ds_write_b128 v138, v[32:35]
	ds_write_b128 v54, v[36:39] offset:37376
	v_add_u32_e32 v58, 0xcc0, v58
	v_add_u32_e32 v6, v57, v58
	v_add_u32_e32 v139, v52, v58
	ds_write_b128 v6, v[24:27]
	ds_write_b128 v139, v[48:51]
	ds_write_b128 v54, v[44:47] offset:38656
	v_bfe_u32 v147, v140, 5, 1
	v_lshrrev_b32_e32 v141, 2, v140
	s_waitcnt vmcnt(0)
	v_mul_f32_e32 v4, 0xbfb8aa3b, v56
	v_fma_f32 v5, v56, s5, -v4
	v_rndne_f32_e32 v7, v4
	v_fmac_f32_e32 v5, 0xb2a5705f, v56
	v_sub_f32_e32 v4, v4, v7
	v_add_f32_e32 v4, v4, v5
	v_cvt_i32_f32_e32 v7, v7
	v_exp_f32_e32 v4, v4
	v_cmp_nlt_f32_e32 vcc, s16, v56
	v_ldexp_f32 v4, v4, v7
	s_nop 0
	v_cndmask_b32_e32 v4, 0, v4, vcc
	v_cmp_ngt_f32_e32 vcc, s21, v56
	s_nop 1
	v_cndmask_b32_e32 v4, v225, v4, vcc
	v_add_f32_e32 v4, 1.0, v4
	v_cmp_gt_f32_e32 vcc, s35, v4
	s_and_b64 s[6:7], vcc, exec
	s_cselect_b32 s5, 32, 0
	s_ashr_i32 s1, s0, 31
	v_ldexp_f32 v4, v4, s5
	s_lshl_b64 s[4:5], s[0:1], s4
	s_ashr_i32 s21, s27, 7
	s_bfe_u32 s22, s27, 0x20005
	s_and_b32 s23, s27, 31
	s_lshl_b32 s16, s20, 7
	s_lshl_b64 s[6:7], s[0:1], 12
	s_lshl_b64 s[4:5], s[4:5], 1
	v_readlane_b32 s1, v253, 33
	s_add_u32 s1, s1, s4
	v_readlane_b32 s4, v253, 32
	s_addc_u32 s4, s4, s5
	s_lshl_b32 s5, s20, 15
	s_lshl_b32 s26, s15, 20
	s_or_b32 s5, s26, s5
	s_add_u32 s28, s1, s5
	s_addc_u32 s29, s4, 0
	s_lshl_b32 s1, s14, 6
	s_and_b32 s26, s1, 64
	v_log_f32_e32 v4, v4
	s_lshl_b32 s30, s14, 4
	s_lshl_b32 s1, s26, 2
	s_or_b32 s6, s6, s16
	s_lshl_b32 s16, s15, 8
	s_lshl_b32 s4, s15, 9
	s_and_b32 s14, s30, 0xffffffe0
	s_add_i32 s1, s1, 0
	s_add_u32 s4, s10, s4
	v_cndmask_b32_e32 v5, 0, v226, vcc
	s_addc_u32 s5, s11, 0
	v_sub_f32_e32 v150, v4, v5
	s_cmp_gt_i32 s27, -1
	v_ashrrev_i32_e32 v145, 31, v144
	v_lshlrev_b64 v[4:5], 8, v[144:145]
	v_lshl_add_u64 v[4:5], s[28:29], 0, v[4:5]
	v_lshl_add_u64 v[4:5], v[4:5], 0, v[2:3]
	s_mov_b32 s27, 0x400000
	v_add_co_u32_e32 v8, vcc, s27, v4
	s_mov_b64 s[28:29], 0x400000
	s_nop 0
	v_addc_co_u32_e32 v9, vcc, 0, v5, vcc
	v_lshl_add_u64 v[6:7], v[4:5], 0, s[28:29]
	global_load_dwordx4 v[72:75], v[4:5], off
	global_load_dwordx4 v[76:79], v[8:9], off
	global_load_dwordx4 v[80:83], v[4:5], off offset:1024
	global_load_dwordx4 v[84:87], v[6:7], off offset:1024
	global_load_dwordx4 v[88:91], v[4:5], off offset:2048
	global_load_dwordx4 v[92:95], v[6:7], off offset:2048
	global_load_dwordx4 v[96:99], v[4:5], off offset:3072
	global_load_dwordx4 v[128:131], v[6:7], off offset:3072
	v_mov_b32_e32 v4, s30
	s_movk_i32 s27, 0xffe0
	v_bfi_b32 v154, s27, v4, v140
	v_mul_lo_u32 v4, v154, s33
	v_lshlrev_b32_e32 v5, 4, v147
	s_waitcnt lgkmcnt(0)
	s_barrier
	s_cselect_b32 s98, 1, 0
	s_cmp_ge_u32 s30, 64
	s_cbranch_scc0 rout_stg_skip1
	s_sleep 17
; #define RLAS __attribute__((address_space(3)))
; #define RMFMA(a, b, c) __builtin_amdgcn_mfma_f32_32x32x16_bf16(a, b, c, 0, 0, 0)
; __device__ __forceinline__ void out_unit(RLAS unsigned char* L, int b, int h, int c, const bf16_t* QR, bf16_t* PR, const bf16_t* KR, const bf16_t* VR, const bf16_t* GR, const bf16_t* ST, size_t stbatch, const float* gnw, float lgf, float lgb, OutRegs& PF, bool is_first, bool has_next, int nb, int nh ...
;     ...
;     bf16x8 qf[8];
; #pragma unroll
;     for (int ks = 0; ks < 8; ++ks) qf[ks] = *(const RLAS bf16x8*)(R2 + (32 * ib + r) * RS + (16 * ks + 8 * h2) * 2);
;     bf16x8 P[4][2];
;     const int iq = 32 * ib + r;
;     float cfm[3], cbp[3];
; #pragma unroll
;     for (int e = 0; e < 3; ++e) { cfm[e] = __builtin_amdgcn_exp2f(-lgf * (float)(e + 1)); cbp[e] = __builtin_amdgcn_exp2f(lgb * (float)(e + 1)); }
;     { f32x16 X[4];
; #pragma unroll
;       for (int jb = 0; jb < 4; ++jb)
; #pragma unroll
;           for (int g = 0; g < 16; ++g) X[jb][g] = 0.f;
; #pragma unroll
;       for (int ks = 0; ks < 8; ++ks) { bf16x8 a[4];
; #pragma unroll
;           for (int jb = 0; jb < 4; ++jb) a[jb] = *(const RLAS bf16x8*)(R0 + (32 * jb + r) * RS + (16 * ks + 8 * h2) * 2);
; #pragma unroll
;           for (int jb = 0; jb < 4; ++jb) X[jb] = RMFMA(a[jb], qf[ks], X[jb]); }
; #pragma unroll
;       for (int jb = 0; jb < 4; ++jb) {
; #pragma unroll
;           for (int q4 = 0; q4 < 4; ++q4) {
;               const int d0 = iq - (32 * jb + 8 * q4 + 4 * h2); const float fd = (float)d0, Ff = __builtin_amdgcn_exp2f(lgf * fd), Fb = __builtin_amdgcn_exp2f(-lgb * fd);
;               X[jb][4 * q4 + 0] *= d0 >= 0 ? Ff : Fb;             X[jb][4 * q4 + 1] *= d0 >= 1 ? Ff * cfm[0] : Fb * cbp[0];
;               X[jb][4 * q4 + 2] *= d0 >= 2 ? Ff * cfm[1] : Fb * cbp[1]; X[jb][4 * q4 + 3] *= d0 >= 3 ? Ff * cfm[2] : Fb * cbp[2]; }
rout_stg_skip1:
	s_cmp_lg_u32 s98, 0
	v_add3_u32 v4, s37, v4, v5
	ds_read_b128 v[68:71], v4
	ds_read_b128 v[124:127], v4 offset:32
	ds_read_b128 v[120:123], v4 offset:64
	ds_read_b128 v[116:119], v4 offset:96
	ds_read_b128 v[112:115], v4 offset:128
	ds_read_b128 v[108:111], v4 offset:160
	ds_read_b128 v[104:107], v4 offset:192
	ds_read_b128 v[100:103], v4 offset:224
	v_add_f32_e32 v4, v149, v149
	v_exp_f32_e32 v132, v4
	v_mul_f32_e32 v4, -2.0, v150
	v_and_b32_e32 v151, 31, v140
	v_exp_f32_e32 v134, v4
	v_mul_f32_e32 v4, 0x40400000, v149
	v_add_u32_e32 v152, 0, v5
	v_exp_f32_e32 v133, v4
	v_mul_f32_e32 v4, 0xc0400000, v150
	v_mad_u32_u24 v153, v151, s33, v152
	v_exp_f32_e32 v135, v4
	ds_read_b128 v[4:7], v153 offset:8704
	ds_read_b128 v[8:11], v153 offset:17408
	ds_read_b128 v[12:15], v153 offset:26112
	ds_read_b128 v[16:19], v153
	ds_read_b128 v[156:159], v153 offset:32
	s_waitcnt lgkmcnt(1)
	v_mfma_f32_32x32x16_bf16 v[52:67], v[16:19], v[68:71], 0
	ds_read_b128 v[160:163], v153 offset:8736
	ds_read_b128 v[164:167], v153 offset:17440
	ds_read_b128 v[168:171], v153 offset:26144
	v_exp_f32_e32 v143, v149
	v_exp_f32_e64 v146, -v150
	v_and_b32_e32 v142, 16, v140
	s_movk_i32 s27, 0x6000
	v_mfma_f32_32x32x16_bf16 v[36:51], v[4:7], v[68:71], 0
	v_mfma_f32_32x32x16_bf16 v[20:35], v[8:11], v[68:71], 0
	v_mfma_f32_32x32x16_bf16 v[4:19], v[12:15], v[68:71], 0
	ds_read_b128 v[172:175], v153 offset:64
	ds_read_b128 v[176:179], v153 offset:8768
	ds_read_b128 v[180:183], v153 offset:17472
	ds_read_b128 v[184:187], v153 offset:26176
	s_waitcnt lgkmcnt(7)
	v_mfma_f32_32x32x16_bf16 v[52:67], v[156:159], v[124:127], v[52:67]
	s_waitcnt lgkmcnt(6)
	v_mfma_f32_32x32x16_bf16 v[36:51], v[160:163], v[124:127], v[36:51]
	s_waitcnt lgkmcnt(5)
	v_mfma_f32_32x32x16_bf16 v[20:35], v[164:167], v[124:127], v[20:35]
	s_waitcnt lgkmcnt(4)
	v_mfma_f32_32x32x16_bf16 v[4:19], v[168:171], v[124:127], v[4:19]
	ds_read_b128 v[156:159], v153 offset:96
	ds_read_b128 v[160:163], v153 offset:8800
	ds_read_b128 v[164:167], v153 offset:17504
	ds_read_b128 v[168:171], v153 offset:26208
	s_waitcnt lgkmcnt(7)
	v_mfma_f32_32x32x16_bf16 v[52:67], v[172:175], v[120:123], v[52:67]
	s_waitcnt lgkmcnt(6)
	v_mfma_f32_32x32x16_bf16 v[36:51], v[176:179], v[120:123], v[36:51]
	s_waitcnt lgkmcnt(5)
	v_mfma_f32_32x32x16_bf16 v[20:35], v[180:183], v[120:123], v[20:35]
	s_waitcnt lgkmcnt(4)
	v_mfma_f32_32x32x16_bf16 v[4:19], v[184:187], v[120:123], v[4:19]
	ds_read_b128 v[172:175], v153 offset:128
	ds_read_b128 v[176:179], v153 offset:8832
	ds_read_b128 v[180:183], v153 offset:17536
	ds_read_b128 v[184:187], v153 offset:26240
	s_waitcnt lgkmcnt(7)
	v_mfma_f32_32x32x16_bf16 v[52:67], v[156:159], v[116:119], v[52:67]
	s_waitcnt lgkmcnt(6)
	v_mfma_f32_32x32x16_bf16 v[36:51], v[160:163], v[116:119], v[36:51]
	s_waitcnt lgkmcnt(5)
	v_mfma_f32_32x32x16_bf16 v[20:35], v[164:167], v[116:119], v[20:35]
	s_waitcnt lgkmcnt(4)
	v_mfma_f32_32x32x16_bf16 v[4:19], v[168:171], v[116:119], v[4:19]
	ds_read_b128 v[156:159], v153 offset:160
	ds_read_b128 v[160:163], v153 offset:8864
	ds_read_b128 v[164:167], v153 offset:17568
	ds_read_b128 v[168:171], v153 offset:26272
	s_waitcnt lgkmcnt(7)
	v_mfma_f32_32x32x16_bf16 v[52:67], v[172:175], v[112:115], v[52:67]
	s_waitcnt lgkmcnt(6)
	v_mfma_f32_32x32x16_bf16 v[36:51], v[176:179], v[112:115], v[36:51]
	s_waitcnt lgkmcnt(5)
	v_mfma_f32_32x32x16_bf16 v[20:35], v[180:183], v[112:115], v[20:35]
	s_waitcnt lgkmcnt(4)
	v_mfma_f32_32x32x16_bf16 v[4:19], v[184:187], v[112:115], v[4:19]
	ds_read_b128 v[172:175], v153 offset:192
	ds_read_b128 v[176:179], v153 offset:8896
	ds_read_b128 v[180:183], v153 offset:17600
	ds_read_b128 v[184:187], v153 offset:26304
	s_waitcnt lgkmcnt(7)
	v_mfma_f32_32x32x16_bf16 v[52:67], v[156:159], v[108:111], v[52:67]
	s_waitcnt lgkmcnt(6)
	v_mfma_f32_32x32x16_bf16 v[36:51], v[160:163], v[108:111], v[36:51]
	s_waitcnt lgkmcnt(5)
	v_mfma_f32_32x32x16_bf16 v[20:35], v[164:167], v[108:111], v[20:35]
	s_waitcnt lgkmcnt(4)
	v_mfma_f32_32x32x16_bf16 v[4:19], v[168:171], v[108:111], v[4:19]
	ds_read_b128 v[156:159], v153 offset:224
	ds_read_b128 v[160:163], v153 offset:8928
	ds_read_b128 v[164:167], v153 offset:17632
	ds_read_b128 v[168:171], v153 offset:26336
	s_waitcnt lgkmcnt(7)
	v_mfma_f32_32x32x16_bf16 v[52:67], v[172:175], v[104:107], v[52:67]
	s_waitcnt lgkmcnt(6)
	v_mfma_f32_32x32x16_bf16 v[36:51], v[176:179], v[104:107], v[36:51]
	s_waitcnt lgkmcnt(5)
	v_mfma_f32_32x32x16_bf16 v[20:35], v[180:183], v[104:107], v[20:35]
	s_waitcnt lgkmcnt(4)
	v_mfma_f32_32x32x16_bf16 v[4:19], v[184:187], v[104:107], v[4:19]
	v_lshlrev_b32_e32 v153, 2, v147
	v_sub_u32_e32 v147, v154, v153
	v_cvt_f32_i32_e32 v155, v147
	v_cmp_gt_i32_e32 vcc, 0, v147
	v_cmp_lt_i32_e64 s[38:39], 0, v147
	v_mul_f32_e64 v154, -v149, v155
	s_waitcnt lgkmcnt(3)
	v_mfma_f32_32x32x16_bf16 v[52:67], v[156:159], v[100:103], v[52:67]
	v_mul_f32_e32 v155, v150, v155
	v_exp_f32_e32 v154, v154
	v_exp_f32_e32 v156, v155
	v_mul_f32_e32 v155, v143, v154
	v_mul_f32_e32 v157, v146, v156
	v_cndmask_b32_e64 v159, v157, v155, s[38:39]
	v_cndmask_b32_e32 v158, v154, v156, vcc
	v_cmp_lt_i32_e32 vcc, 1, v147
	v_cmp_lt_i32_e64 s[38:39], 2, v147
	v_pk_mul_f32 v[154:155], v[132:133], v[154:155] op_sel_hi:[1,0]
	v_pk_mul_f32 v[156:157], v[134:135], v[156:157] op_sel_hi:[1,0]
	s_nop 0
	v_pk_mul_f32 v[52:53], v[158:159], v[52:53]
	v_cndmask_b32_e64 v155, v157, v155, s[38:39]
	v_cndmask_b32_e32 v154, v156, v154, vcc
	v_pk_mul_f32 v[54:55], v[154:155], v[54:55]
	v_add_u32_e32 v155, -8, v147
	v_cvt_f32_i32_e32 v156, v155
	v_cmp_gt_i32_e32 vcc, 0, v155
	v_cmp_lt_i32_e64 s[38:39], 0, v155
	s_waitcnt lgkmcnt(2)
; __device__ __forceinline__ unsigned pkbf(float lo, float hi) { const f32x2r v = {lo, hi}; return __builtin_bit_cast(unsigned, __builtin_convertvector(v, bf16x2r)); }
; __device__ __forceinline__ void out_unit(RLAS unsigned char* L, int b, int h, int c, const bf16_t* QR, bf16_t* PR, const bf16_t* KR, const bf16_t* VR, const bf16_t* GR, const bf16_t* ST, size_t stbatch, const float* gnw, float lgf, float lgb, OutRegs& PF, bool is_first, bool has_next, int nb, int nh ...
;     ...
;       for (int jb = 0; jb < 4; ++jb) {
; #pragma unroll
;           for (int q4 = 0; q4 < 4; ++q4) {
;               const int d0 = iq - (32 * jb + 8 * q4 + 4 * h2); const float fd = (float)d0, Ff = __builtin_amdgcn_exp2f(lgf * fd), Fb = __builtin_amdgcn_exp2f(-lgb * fd);
;               X[jb][4 * q4 + 0] *= d0 >= 0 ? Ff : Fb;             X[jb][4 * q4 + 1] *= d0 >= 1 ? Ff * cfm[0] : Fb * cbp[0];
;               X[jb][4 * q4 + 2] *= d0 >= 2 ? Ff * cfm[1] : Fb * cbp[1]; X[jb][4 * q4 + 3] *= d0 >= 3 ? Ff * cfm[2] : Fb * cbp[2]; }
; #pragma unroll
;           for (int s = 0; s < 2; ++s) { u32x4 pw; pw.x = pkbf(X[jb][8 * s + 0], X[jb][8 * s + 1]); pw.y = pkbf(X[jb][8 * s + 2], X[jb][8 * s + 3]); pw.z = pkbf(X[jb][8 * s + 4], X[jb][8 * s + 5]); pw.w = pkbf(X[jb][8 * s + 6], X[jb][8 * s + 7]);
;               P[jb][s] = __builtin_bit_cast(bf16x8, pw); } } }
	v_mfma_f32_32x32x16_bf16 v[36:51], v[160:163], v[100:103], v[36:51]
	v_mul_f32_e64 v154, -v149, v156
	v_mul_f32_e32 v156, v150, v156
	v_exp_f32_e32 v154, v154
	v_exp_f32_e32 v156, v156
	v_mul_f32_e32 v157, v143, v154
	v_mul_f32_e32 v158, v146, v156
	v_cndmask_b32_e64 v159, v158, v157, s[38:39]
	v_cndmask_b32_e32 v158, v154, v156, vcc
	v_pk_mul_f32 v[158:159], v[158:159], v[56:57]
	v_cmp_lt_i32_e32 vcc, 1, v155
	v_cmp_lt_i32_e64 s[38:39], 2, v155
	v_pk_mul_f32 v[56:57], v[132:133], v[154:155] op_sel_hi:[1,0]
	v_pk_mul_f32 v[154:155], v[134:135], v[156:157] op_sel_hi:[1,0]
	s_waitcnt lgkmcnt(1)
	v_mfma_f32_32x32x16_bf16 v[20:35], v[164:167], v[100:103], v[20:35]
	v_cndmask_b32_e64 v57, v155, v57, s[38:39]
	v_cndmask_b32_e32 v56, v154, v56, vcc
	v_mul_f32_e64 v154, v56, v58
	v_mul_f32_e64 v155, v57, v59
	v_add_u32_e32 v57, -16, v147
	v_cvt_f32_i32_e32 v58, v57
	v_cmp_gt_i32_e32 vcc, 0, v57
	v_cmp_lt_i32_e64 s[38:39], 0, v57
	s_waitcnt lgkmcnt(0)
	v_mfma_f32_32x32x16_bf16 v[4:19], v[168:171], v[100:103], v[4:19]
	v_mul_f32_e64 v56, -v149, v58
	v_mul_f32_e32 v58, v150, v58
	v_exp_f32_e32 v56, v56
	v_exp_f32_e32 v58, v58
	v_mul_f32_e32 v59, v143, v56
	v_mul_f32_e32 v156, v146, v58
	v_cndmask_b32_e64 v157, v156, v59, s[38:39]
	v_cndmask_b32_e32 v156, v56, v58, vcc
	v_cmp_lt_i32_e32 vcc, 1, v57
	v_cmp_lt_i32_e64 s[38:39], 2, v57
	v_pk_mul_f32 v[56:57], v[132:133], v[56:57] op_sel_hi:[1,0]
	v_pk_mul_f32 v[58:59], v[134:135], v[58:59] op_sel_hi:[1,0]
	v_pk_mul_f32 v[60:61], v[156:157], v[60:61]
	v_cndmask_b32_e64 v57, v59, v57, s[38:39]
	v_cndmask_b32_e32 v56, v58, v56, vcc
	v_pk_mul_f32 v[62:63], v[56:57], v[62:63]
	v_subrev_u32_e32 v57, 24, v147
	v_cvt_f32_i32_e32 v58, v57
	v_cmp_gt_i32_e32 vcc, 0, v57
	v_cmp_lt_i32_e64 s[38:39], 0, v57
	v_mul_f32_e64 v56, -v149, v58
	v_mul_f32_e32 v58, v150, v58
	v_exp_f32_e32 v56, v56
	v_exp_f32_e32 v58, v58
	v_mul_f32_e32 v59, v143, v56
	v_mul_f32_e32 v156, v146, v58
	v_cndmask_b32_e64 v157, v156, v59, s[38:39]
	v_cndmask_b32_e32 v156, v56, v58, vcc
	v_cmp_lt_i32_e32 vcc, 1, v57
	v_cmp_lt_i32_e64 s[38:39], 2, v57
	v_pk_mul_f32 v[56:57], v[132:133], v[56:57] op_sel_hi:[1,0]
	v_pk_mul_f32 v[58:59], v[134:135], v[58:59] op_sel_hi:[1,0]
	v_pk_mul_f32 v[64:65], v[156:157], v[64:65]
	v_cndmask_b32_e64 v57, v59, v57, s[38:39]
	v_cndmask_b32_e32 v56, v58, v56, vcc
	v_pk_mul_f32 v[66:67], v[56:57], v[66:67]
	v_cvt_pk_bf16_f32 v56, v52, v53
	v_cvt_pk_bf16_f32 v52, v60, v61
	v_subrev_u32_e32 v61, 32, v147
	v_cvt_pk_bf16_f32 v53, v62, v63
	v_cvt_f32_i32_e32 v62, v61
	v_cvt_pk_bf16_f32 v57, v54, v55
	v_cvt_pk_bf16_f32 v54, v64, v65
	v_cmp_gt_i32_e32 vcc, 0, v61
	v_mul_f32_e64 v60, -v149, v62
	v_mul_f32_e32 v62, v150, v62
	v_exp_f32_e32 v60, v60
	v_exp_f32_e32 v62, v62
	v_cmp_lt_i32_e64 s[38:39], 0, v61
	v_cvt_pk_bf16_f32 v58, v158, v159
	v_mul_f32_e32 v63, v143, v60
	v_mul_f32_e32 v64, v146, v62
	v_cndmask_b32_e64 v65, v64, v63, s[38:39]
	v_cndmask_b32_e32 v64, v60, v62, vcc
	v_cmp_lt_i32_e32 vcc, 1, v61
	v_cmp_lt_i32_e64 s[38:39], 2, v61
	v_pk_mul_f32 v[60:61], v[132:133], v[60:61] op_sel_hi:[1,0]
	v_pk_mul_f32 v[62:63], v[134:135], v[62:63] op_sel_hi:[1,0]
	v_pk_mul_f32 v[36:37], v[64:65], v[36:37]
	v_cndmask_b32_e64 v61, v63, v61, s[38:39]
	v_cndmask_b32_e32 v60, v62, v60, vcc
	v_pk_mul_f32 v[38:39], v[60:61], v[38:39]
	v_subrev_u32_e32 v61, 40, v147
	v_cvt_f32_i32_e32 v62, v61
	v_cmp_gt_i32_e32 vcc, 0, v61
	v_cmp_lt_i32_e64 s[38:39], 0, v61
	v_cvt_pk_bf16_f32 v59, v154, v155
	v_mul_f32_e64 v60, -v149, v62
	v_mul_f32_e32 v62, v150, v62
	v_exp_f32_e32 v60, v60
	v_exp_f32_e32 v62, v62
	v_cvt_pk_bf16_f32 v55, v66, v67
	v_mul_f32_e32 v63, v143, v60
	v_mul_f32_e32 v64, v146, v62
	v_cndmask_b32_e64 v65, v64, v63, s[38:39]
	v_cndmask_b32_e32 v64, v60, v62, vcc
	v_pk_mul_f32 v[64:65], v[64:65], v[40:41]
	v_cmp_lt_i32_e32 vcc, 1, v61
	v_cmp_lt_i32_e64 s[38:39], 2, v61
	v_pk_mul_f32 v[40:41], v[132:133], v[60:61] op_sel_hi:[1,0]
	v_pk_mul_f32 v[60:61], v[134:135], v[62:63] op_sel_hi:[1,0]
	s_nop 0
	v_cndmask_b32_e64 v41, v61, v41, s[38:39]
	v_cndmask_b32_e32 v40, v60, v40, vcc
	v_pk_mul_f32 v[60:61], v[40:41], v[42:43]
	v_subrev_u32_e32 v41, 48, v147
	v_cvt_f32_i32_e32 v42, v41
	v_cmp_gt_i32_e32 vcc, 0, v41
	v_cmp_lt_i32_e64 s[38:39], 0, v41
	v_mul_f32_e64 v40, -v149, v42
	v_mul_f32_e32 v42, v150, v42
	v_exp_f32_e32 v40, v40
	v_exp_f32_e32 v42, v42
	v_mul_f32_e32 v43, v143, v40
	v_mul_f32_e32 v62, v146, v42
	v_cndmask_b32_e64 v63, v62, v43, s[38:39]
	v_cndmask_b32_e32 v62, v40, v42, vcc
	v_cmp_lt_i32_e32 vcc, 1, v41
	v_cmp_lt_i32_e64 s[38:39], 2, v41
	v_pk_mul_f32 v[40:41], v[132:133], v[40:41] op_sel_hi:[1,0]
	v_pk_mul_f32 v[42:43], v[134:135], v[42:43] op_sel_hi:[1,0]
	v_pk_mul_f32 v[44:45], v[62:63], v[44:45]
	v_cndmask_b32_e64 v41, v43, v41, s[38:39]
	v_cndmask_b32_e32 v40, v42, v40, vcc
	v_pk_mul_f32 v[46:47], v[40:41], v[46:47]
	v_subrev_u32_e32 v41, 56, v147
	v_cvt_f32_i32_e32 v42, v41
	v_cmp_gt_i32_e32 vcc, 0, v41
	v_cmp_lt_i32_e64 s[38:39], 0, v41
	v_mul_f32_e64 v40, -v149, v42
	v_mul_f32_e32 v42, v150, v42
	v_exp_f32_e32 v40, v40
	v_exp_f32_e32 v42, v42
	v_mul_f32_e32 v43, v143, v40
	v_mul_f32_e32 v62, v146, v42
	v_cndmask_b32_e64 v63, v62, v43, s[38:39]
	v_cndmask_b32_e32 v62, v40, v42, vcc
	v_cmp_lt_i32_e32 vcc, 1, v41
	v_cmp_lt_i32_e64 s[38:39], 2, v41
	v_pk_mul_f32 v[40:41], v[132:133], v[40:41] op_sel_hi:[1,0]
	v_pk_mul_f32 v[42:43], v[134:135], v[42:43] op_sel_hi:[1,0]
	v_pk_mul_f32 v[48:49], v[62:63], v[48:49]
	v_cndmask_b32_e64 v41, v43, v41, s[38:39]
	v_cndmask_b32_e32 v40, v42, v40, vcc
	v_pk_mul_f32 v[50:51], v[40:41], v[50:51]
	v_cvt_pk_bf16_f32 v40, v36, v37
	v_cvt_pk_bf16_f32 v36, v44, v45
; __device__ __forceinline__ unsigned pkbf(float lo, float hi) { const f32x2r v = {lo, hi}; return __builtin_bit_cast(unsigned, __builtin_convertvector(v, bf16x2r)); }
; __device__ __forceinline__ void out_unit(RLAS unsigned char* L, int b, int h, int c, const bf16_t* QR, bf16_t* PR, const bf16_t* KR, const bf16_t* VR, const bf16_t* GR, const bf16_t* ST, size_t stbatch, const float* gnw, float lgf, float lgb, OutRegs& PF, bool is_first, bool has_next, int nb, int nh ...
;     ...
;       for (int jb = 0; jb < 4; ++jb) {
; #pragma unroll
;           for (int q4 = 0; q4 < 4; ++q4) {
;               const int d0 = iq - (32 * jb + 8 * q4 + 4 * h2); const float fd = (float)d0, Ff = __builtin_amdgcn_exp2f(lgf * fd), Fb = __builtin_amdgcn_exp2f(-lgb * fd);
;               X[jb][4 * q4 + 0] *= d0 >= 0 ? Ff : Fb;             X[jb][4 * q4 + 1] *= d0 >= 1 ? Ff * cfm[0] : Fb * cbp[0];
;               X[jb][4 * q4 + 2] *= d0 >= 2 ? Ff * cfm[1] : Fb * cbp[1]; X[jb][4 * q4 + 3] *= d0 >= 3 ? Ff * cfm[2] : Fb * cbp[2]; }
; #pragma unroll
;           for (int s = 0; s < 2; ++s) { u32x4 pw; pw.x = pkbf(X[jb][8 * s + 0], X[jb][8 * s + 1]); pw.y = pkbf(X[jb][8 * s + 2], X[jb][8 * s + 3]); pw.z = pkbf(X[jb][8 * s + 4], X[jb][8 * s + 5]); pw.w = pkbf(X[jb][8 * s + 6], X[jb][8 * s + 7]);
;               P[jb][s] = __builtin_bit_cast(bf16x8, pw); } } }
;     f32x16 Z[2];
; #pragma unroll
;     for (int t = 0; t < 2; ++t)
; #pragma unroll
;         for (int g = 0; g < 16; ++g) Z[t][g] = 0.f;
;     { const int cb0 = (64 * dvh + 16 * gq + 4 * p) * 2;
; #pragma unroll
;       for (int jb = 0; jb < 4; ++jb)
; #pragma unroll
;           for (int s = 0; s < 2; ++s) { const bf16x8 v0 = trfragv(R1, 32 * jb + 16 * s + 4 * h2 + q, 8, cb0), v1 = trfragv(R1, 32 * jb + 16 * s + 4 * h2 + q, 8, cb0 + 64);
	v_subrev_u32_e32 v45, 64, v147
	v_cvt_pk_bf16_f32 v37, v46, v47
	v_cvt_f32_i32_e32 v46, v45
	v_cvt_pk_bf16_f32 v41, v38, v39
	v_cvt_pk_bf16_f32 v38, v48, v49
	v_cmp_gt_i32_e32 vcc, 0, v45
	v_mul_f32_e64 v44, -v149, v46
	v_mul_f32_e32 v46, v150, v46
	v_exp_f32_e32 v44, v44
	v_exp_f32_e32 v46, v46
	v_cmp_lt_i32_e64 s[38:39], 0, v45
	v_cvt_pk_bf16_f32 v43, v60, v61
	v_mul_f32_e32 v47, v143, v44
	v_mul_f32_e32 v48, v146, v46
	v_cndmask_b32_e64 v49, v48, v47, s[38:39]
	v_cndmask_b32_e32 v48, v44, v46, vcc
	v_cmp_lt_i32_e32 vcc, 1, v45
	v_cmp_lt_i32_e64 s[38:39], 2, v45
	v_pk_mul_f32 v[44:45], v[132:133], v[44:45] op_sel_hi:[1,0]
	v_pk_mul_f32 v[46:47], v[134:135], v[46:47] op_sel_hi:[1,0]
	v_pk_mul_f32 v[20:21], v[48:49], v[20:21]
	v_cndmask_b32_e64 v45, v47, v45, s[38:39]
	v_cndmask_b32_e32 v44, v46, v44, vcc
	v_pk_mul_f32 v[22:23], v[44:45], v[22:23]
	v_add_u32_e32 v45, 0xffffffb8, v147
	v_cvt_f32_i32_e32 v46, v45
	v_cmp_gt_i32_e32 vcc, 0, v45
	v_cmp_lt_i32_e64 s[38:39], 0, v45
	v_cvt_pk_bf16_f32 v60, v20, v21
	v_mul_f32_e64 v44, -v149, v46
	v_mul_f32_e32 v46, v150, v46
	v_exp_f32_e32 v44, v44
	v_exp_f32_e32 v46, v46
	v_add_u32_e32 v21, 0xffffffa0, v147
	v_cvt_pk_bf16_f32 v61, v22, v23
	v_mul_f32_e32 v47, v143, v44
	v_mul_f32_e32 v48, v146, v46
	v_cndmask_b32_e64 v49, v48, v47, s[38:39]
	v_cndmask_b32_e32 v48, v44, v46, vcc
	v_cmp_lt_i32_e32 vcc, 1, v45
	v_cmp_lt_i32_e64 s[38:39], 2, v45
	v_pk_mul_f32 v[44:45], v[132:133], v[44:45] op_sel_hi:[1,0]
	v_pk_mul_f32 v[46:47], v[134:135], v[46:47] op_sel_hi:[1,0]
	v_pk_mul_f32 v[24:25], v[48:49], v[24:25]
	v_cndmask_b32_e64 v45, v47, v45, s[38:39]
	v_cndmask_b32_e32 v44, v46, v44, vcc
	v_pk_mul_f32 v[26:27], v[44:45], v[26:27]
	v_add_u32_e32 v45, 0xffffffb0, v147
	v_cvt_f32_i32_e32 v46, v45
	v_cmp_gt_i32_e32 vcc, 0, v45
	v_cmp_lt_i32_e64 s[38:39], 0, v45
	v_cvt_f32_i32_e32 v22, v21
	v_mul_f32_e64 v44, -v149, v46
	v_mul_f32_e32 v46, v150, v46
	v_exp_f32_e32 v44, v44
	v_exp_f32_e32 v46, v46
	v_mul_f32_e64 v20, -v149, v22
	v_mul_f32_e32 v22, v150, v22
	v_mul_f32_e32 v47, v143, v44
	v_mul_f32_e32 v48, v146, v46
	v_cndmask_b32_e64 v49, v48, v47, s[38:39]
	v_cndmask_b32_e32 v48, v44, v46, vcc
	v_cmp_lt_i32_e32 vcc, 1, v45
	v_cmp_lt_i32_e64 s[38:39], 2, v45
	v_pk_mul_f32 v[44:45], v[132:133], v[44:45] op_sel_hi:[1,0]
	v_pk_mul_f32 v[46:47], v[134:135], v[46:47] op_sel_hi:[1,0]
	v_exp_f32_e32 v20, v20
	v_cndmask_b32_e64 v45, v47, v45, s[38:39]
	v_cndmask_b32_e32 v44, v46, v44, vcc
	v_pk_mul_f32 v[30:31], v[44:45], v[30:31]
	v_add_u32_e32 v45, 0xffffffa8, v147
	v_cvt_f32_i32_e32 v46, v45
	v_exp_f32_e32 v22, v22
	v_pk_mul_f32 v[28:29], v[48:49], v[28:29]
	v_cmp_gt_i32_e32 vcc, 0, v45
	v_mul_f32_e64 v44, -v149, v46
	v_mul_f32_e32 v46, v150, v46
	v_exp_f32_e32 v44, v44
	v_exp_f32_e32 v46, v46
	v_cmp_lt_i32_e64 s[38:39], 0, v45
	v_cvt_pk_bf16_f32 v62, v24, v25
	v_mul_f32_e32 v47, v143, v44
	v_mul_f32_e32 v48, v146, v46
	v_cndmask_b32_e64 v49, v48, v47, s[38:39]
	v_cndmask_b32_e32 v48, v44, v46, vcc
	v_cmp_lt_i32_e32 vcc, 1, v45
	v_cmp_lt_i32_e64 s[38:39], 2, v45
	v_pk_mul_f32 v[44:45], v[132:133], v[44:45] op_sel_hi:[1,0]
	v_pk_mul_f32 v[46:47], v[134:135], v[46:47] op_sel_hi:[1,0]
	v_mul_f32_e32 v23, v143, v20
	v_cndmask_b32_e64 v45, v47, v45, s[38:39]
	v_cndmask_b32_e32 v44, v46, v44, vcc
	v_mul_f32_e32 v24, v146, v22
	v_cmp_gt_i32_e32 vcc, 0, v21
	v_cmp_lt_i32_e64 s[38:39], 0, v21
	v_cvt_pk_bf16_f32 v42, v64, v65
	v_cvt_pk_bf16_f32 v39, v50, v51
	v_cndmask_b32_e64 v25, v24, v23, s[38:39]
	v_cndmask_b32_e32 v24, v20, v22, vcc
	v_cmp_lt_i32_e32 vcc, 1, v21
	v_cmp_lt_i32_e64 s[38:39], 2, v21
	v_pk_mul_f32 v[20:21], v[132:133], v[20:21] op_sel_hi:[1,0]
	v_pk_mul_f32 v[22:23], v[134:135], v[22:23] op_sel_hi:[1,0]
	v_pk_mul_f32 v[4:5], v[24:25], v[4:5]
	v_cndmask_b32_e64 v21, v23, v21, s[38:39]
	v_cndmask_b32_e32 v20, v22, v20, vcc
	v_pk_mul_f32 v[6:7], v[20:21], v[6:7]
	v_add_u32_e32 v21, 0xffffff98, v147
	v_cvt_f32_i32_e32 v22, v21
	v_cmp_gt_i32_e32 vcc, 0, v21
	v_cmp_lt_i32_e64 s[38:39], 0, v21
	v_cvt_pk_bf16_f32 v64, v4, v5
	v_mul_f32_e64 v20, -v149, v22
	v_mul_f32_e32 v22, v150, v22
	v_exp_f32_e32 v20, v20
	v_exp_f32_e32 v22, v22
	v_lshlrev_b32_e32 v4, 2, v140
	v_and_b32_e32 v4, 12, v4
	v_mul_f32_e32 v23, v143, v20
	v_mul_f32_e32 v24, v146, v22
	v_cndmask_b32_e64 v25, v24, v23, s[38:39]
	v_cndmask_b32_e32 v24, v20, v22, vcc
	v_cmp_lt_i32_e32 vcc, 1, v21
	v_cmp_lt_i32_e64 s[38:39], 2, v21
	v_pk_mul_f32 v[20:21], v[132:133], v[20:21] op_sel_hi:[1,0]
	v_pk_mul_f32 v[22:23], v[134:135], v[22:23] op_sel_hi:[1,0]
	v_pk_mul_f32 v[8:9], v[24:25], v[8:9]
	v_cndmask_b32_e64 v21, v23, v21, s[38:39]
	v_cndmask_b32_e32 v20, v22, v20, vcc
	v_pk_mul_f32 v[10:11], v[20:21], v[10:11]
	v_add_u32_e32 v21, 0xffffff90, v147
	v_cvt_f32_i32_e32 v22, v21
	v_cmp_gt_i32_e32 vcc, 0, v21
	v_cmp_lt_i32_e64 s[38:39], 0, v21
	v_or3_b32 v4, v4, v142, s26
	v_mul_f32_e64 v20, -v149, v22
	v_mul_f32_e32 v22, v150, v22
	v_exp_f32_e32 v20, v20
	v_exp_f32_e32 v22, v22
	v_and_or_b32 v5, v141, 3, v153
	v_lshlrev_b32_e32 v4, 1, v4
	v_mul_f32_e32 v23, v143, v20
	v_mul_f32_e32 v24, v146, v22
	v_cndmask_b32_e64 v25, v24, v23, s[38:39]
	v_cndmask_b32_e32 v24, v20, v22, vcc
	v_cmp_lt_i32_e32 vcc, 1, v21
	v_cmp_lt_i32_e64 s[38:39], 2, v21
	v_pk_mul_f32 v[20:21], v[132:133], v[20:21] op_sel_hi:[1,0]
	v_pk_mul_f32 v[22:23], v[134:135], v[22:23] op_sel_hi:[1,0]
	v_pk_mul_f32 v[12:13], v[24:25], v[12:13]
	v_cndmask_b32_e64 v21, v23, v21, s[38:39]
	v_cndmask_b32_e32 v20, v22, v20, vcc
	v_pk_mul_f32 v[14:15], v[20:21], v[14:15]
	v_add_u32_e32 v21, 0xffffff88, v147
	v_cvt_f32_i32_e32 v22, v21
	v_cmp_gt_i32_e32 vcc, 0, v21
	v_cmp_lt_i32_e64 s[38:39], 0, v21
	v_mul_u32_u24_e32 v5, 0x140, v5
	v_mul_f32_e64 v20, -v149, v22
	v_mul_f32_e32 v22, v150, v22
	v_exp_f32_e32 v20, v20
	v_exp_f32_e32 v22, v22
	v_add3_u32 v140, 0, v5, v4
	v_cvt_pk_bf16_f32 v65, v6, v7
	v_mul_f32_e32 v23, v143, v20
	v_mul_f32_e32 v24, v146, v22
	v_cndmask_b32_e64 v25, v24, v23, s[38:39]
	v_cndmask_b32_e32 v24, v20, v22, vcc
	v_cmp_lt_i32_e32 vcc, 1, v21
	v_cmp_lt_i32_e64 s[38:39], 2, v21
	v_pk_mul_f32 v[20:21], v[132:133], v[20:21] op_sel_hi:[1,0]
	v_pk_mul_f32 v[22:23], v[134:135], v[22:23] op_sel_hi:[1,0]
	v_pk_mul_f32 v[16:17], v[24:25], v[16:17]
	v_cndmask_b32_e64 v21, v23, v21, s[38:39]
	v_cndmask_b32_e32 v20, v22, v20, vcc
	v_pk_mul_f32 v[18:19], v[20:21], v[18:19]
	ds_read_b64_tr_b16 v[4:5], v140 offset:34816
	ds_read_b64_tr_b16 v[6:7], v140 offset:37376
	ds_read_b64_tr_b16 v[20:21], v140 offset:34880
	ds_read_b64_tr_b16 v[22:23], v140 offset:37440
	ds_read_b64_tr_b16 v[172:173], v140 offset:39936
	ds_read_b64_tr_b16 v[174:175], v140 offset:42496
	ds_read_b64_tr_b16 v[176:177], v140 offset:40000
	ds_read_b64_tr_b16 v[178:179], v140 offset:42560
	v_pk_mul_f32 v[32:33], v[48:49], v[32:33]
	v_cvt_pk_bf16_f32 v66, v8, v9
	v_cvt_pk_bf16_f32 v67, v10, v11
	v_cvt_pk_bf16_f32 v48, v12, v13
	v_cvt_pk_bf16_f32 v49, v14, v15
	v_cvt_pk_bf16_f32 v50, v16, v17
	v_cvt_pk_bf16_f32 v51, v18, v19
	s_waitcnt lgkmcnt(6)
; #define RLAS __attribute__((address_space(3)))
; #define LBAR() do { asm volatile("s_waitcnt lgkmcnt(0)" ::: "memory"); __builtin_amdgcn_s_barrier(); asm volatile("" ::: "memory"); } while (0)
; #define RMFMA(a, b, c) __builtin_amdgcn_mfma_f32_32x32x16_bf16(a, b, c, 0, 0, 0)
; __device__ __forceinline__ void out_unit(RLAS unsigned char* L, int b, int h, int c, const bf16_t* QR, bf16_t* PR, const bf16_t* KR, const bf16_t* VR, const bf16_t* GR, const bf16_t* ST, size_t stbatch, const float* gnw, float lgf, float lgb, OutRegs& PF, bool is_first, bool has_next, int nb, int nh ...
;     ...
;     { const int cb0 = (64 * dvh + 16 * gq + 4 * p) * 2;
; #pragma unroll
;       for (int jb = 0; jb < 4; ++jb)
; #pragma unroll
;           for (int s = 0; s < 2; ++s) { const bf16x8 v0 = trfragv(R1, 32 * jb + 16 * s + 4 * h2 + q, 8, cb0), v1 = trfragv(R1, 32 * jb + 16 * s + 4 * h2 + q, 8, cb0 + 64);
;               Z[0] = RMFMA(P[jb][s], v0, Z[0]); Z[1] = RMFMA(P[jb][s], v1, Z[1]); } }
;     LBAR();
; #pragma unroll
;     for (int i = 0; i < 4; ++i) { *(RLAS u32x4*)(R0 + (grow + 4 * i) * RS + gch * 16) = sfr[i]; *(RLAS u32x4*)(R1 + (grow + 4 * i) * RS + gch * 16) = sbr[i]; }
;     LBAR();
;     u32x4 gwr[4];
;     { const bf16_t* gp0 = GR + (tok0 + grow) * GRP + h * 128 + gch * 8;
; #pragma unroll
;       for (int i = 0; i < 4; ++i) gwr[i] = *(const u32x4*)(gp0 + (size_t)(4 * i) * GRP); }
;     { f32x16 Yf[2], Yb[2];
; #pragma unroll
;       for (int t = 0; t < 2; ++t)
; #pragma unroll
;           for (int g = 0; g < 16; ++g) { Yf[t][g] = 0.f; Yb[t][g] = 0.f; }
;       const int rb0 = (64 * dvh + r) * RS + 16 * h2;
; #pragma unroll
;       for (int ks = 0; ks < 8; ++ks) {
;           const bf16x8 f0 = *(const RLAS bf16x8*)(R0 + rb0 + 32 * ks), f1 = *(const RLAS bf16x8*)(R0 + rb0 + 32 * RS + 32 * ks), b0 = *(const RLAS bf16x8*)(R1 + rb0 + 32 * ks), b1 = *(const RLAS bf16x8*)(R1 + rb0 + 32 * RS + 32 * ks);
;           Yf[0] = RMFMA(qf[ks], f0, Yf[0]); Yf[1] = RMFMA(qf[ks], f1, Yf[1]); Yb[0] = RMFMA(qf[ks], b0, Yb[0]); Yb[1] = RMFMA(qf[ks], b1, Yb[1]); }
	v_mfma_f32_32x32x16_bf16 v[4:19], v[56:59], v[4:7], 0
	v_mul_f32_e64 v34, v44, v34
	v_mul_f32_e64 v35, v45, v35
	v_cvt_pk_bf16_f32 v63, v26, v27
	v_cvt_pk_bf16_f32 v44, v28, v29
	v_cvt_pk_bf16_f32 v45, v30, v31
	v_cvt_pk_bf16_f32 v46, v32, v33
	v_cvt_pk_bf16_f32 v47, v34, v35
	v_add_u32_e32 v141, 0x8800, v140
	s_waitcnt lgkmcnt(4)
	v_mfma_f32_32x32x16_bf16 v[20:35], v[56:59], v[20:23], 0
	ds_read_b64_tr_b16 v[180:181], v140 offset:45056
	ds_read_b64_tr_b16 v[182:183], v140 offset:47616
	ds_read_b64_tr_b16 v[184:185], v140 offset:45120
	ds_read_b64_tr_b16 v[186:187], v140 offset:47680
	s_waitcnt lgkmcnt(6)
	v_mfma_f32_32x32x16_bf16 v[4:19], v[52:55], v[172:175], v[4:19]
	s_waitcnt lgkmcnt(4)
	v_mfma_f32_32x32x16_bf16 v[20:35], v[52:55], v[176:179], v[20:35]
	ds_read_b64_tr_b16 v[172:173], v140 offset:50176
	ds_read_b64_tr_b16 v[174:175], v140 offset:52736
	ds_read_b64_tr_b16 v[176:177], v140 offset:50240
	ds_read_b64_tr_b16 v[178:179], v140 offset:52800
	s_waitcnt lgkmcnt(6)
	v_mfma_f32_32x32x16_bf16 v[4:19], v[40:43], v[180:183], v[4:19]
	s_waitcnt lgkmcnt(4)
	v_mfma_f32_32x32x16_bf16 v[20:35], v[40:43], v[184:187], v[20:35]
	ds_read_b64_tr_b16 v[180:181], v140 offset:55296
	ds_read_b64_tr_b16 v[182:183], v140 offset:57856
	ds_read_b64_tr_b16 v[184:185], v140 offset:55360
	ds_read_b64_tr_b16 v[186:187], v140 offset:57920
	s_waitcnt lgkmcnt(6)
	v_mfma_f32_32x32x16_bf16 v[4:19], v[36:39], v[172:175], v[4:19]
	s_waitcnt lgkmcnt(4)
	v_mfma_f32_32x32x16_bf16 v[20:35], v[36:39], v[176:179], v[20:35]
	ds_read_b64_tr_b16 v[172:173], v140 offset:60416
	ds_read_b64_tr_b16 v[174:175], v140 offset:62976
	ds_read_b64_tr_b16 v[176:177], v140 offset:60480
	ds_read_b64_tr_b16 v[178:179], v140 offset:63040
	s_waitcnt lgkmcnt(6)
	v_mfma_f32_32x32x16_bf16 v[4:19], v[60:63], v[180:183], v[4:19]
	s_waitcnt lgkmcnt(4)
	v_mfma_f32_32x32x16_bf16 v[20:35], v[60:63], v[184:187], v[20:35]
	ds_read_b64_tr_b16 v[180:181], v141 offset:30720
	ds_read_b64_tr_b16 v[182:183], v141 offset:33280
	ds_read_b64_tr_b16 v[184:185], v141 offset:30784
	ds_read_b64_tr_b16 v[186:187], v141 offset:33344
	s_waitcnt lgkmcnt(6)
	v_mfma_f32_32x32x16_bf16 v[4:19], v[44:47], v[172:175], v[4:19]
	s_waitcnt lgkmcnt(4)
	v_mfma_f32_32x32x16_bf16 v[20:35], v[44:47], v[176:179], v[20:35]
	ds_read_b64_tr_b16 v[36:37], v141 offset:35840
	ds_read_b64_tr_b16 v[38:39], v141 offset:38400
	ds_read_b64_tr_b16 v[40:41], v141 offset:35904
	ds_read_b64_tr_b16 v[42:43], v141 offset:38464
	s_waitcnt lgkmcnt(6)
	v_mfma_f32_32x32x16_bf16 v[4:19], v[64:67], v[180:183], v[4:19]
	s_waitcnt lgkmcnt(4)
	v_mfma_f32_32x32x16_bf16 v[20:35], v[64:67], v[184:187], v[20:35]
	s_waitcnt lgkmcnt(0)
	s_barrier
	s_waitcnt vmcnt(7)
	ds_write_b128 v136, v[72:75]
	s_waitcnt vmcnt(6)
	ds_write_b128 v136, v[76:79] offset:34816
	s_waitcnt vmcnt(5)
	ds_write_b128 v137, v[80:83]
	s_waitcnt vmcnt(4)
	ds_write_b128 v137, v[84:87] offset:34816
	s_waitcnt vmcnt(3)
	ds_write_b128 v138, v[88:91]
	s_waitcnt vmcnt(2)
	ds_write_b128 v138, v[92:95] offset:34816
	s_waitcnt vmcnt(1)
	ds_write_b128 v139, v[96:99]
	s_waitcnt vmcnt(0)
	ds_write_b128 v139, v[128:131] offset:34816
	s_waitcnt lgkmcnt(0)
	s_barrier
	s_waitcnt lgkmcnt(10)
	v_mfma_f32_32x32x16_bf16 v[4:19], v[48:51], v[36:39], v[4:19]
	v_lshl_add_u64 v[36:37], s[6:7], 0, v[144:145]
	v_readlane_b32 s6, v252, 32
	v_lshlrev_b64 v[146:147], 11, v[36:37]
	v_readlane_b32 s7, v252, 33
	s_nop 1
	v_lshl_add_u64 v[36:37], s[6:7], 0, v[146:147]
	v_lshl_add_u64 v[36:37], v[36:37], 0, s[16:17]
	v_lshl_add_u64 v[36:37], v[36:37], 0, v[2:3]
	s_movk_i32 s7, 0x2000
	v_add_co_u32_e32 v38, vcc, s7, v36
	s_movk_i32 s6, 0x4000
	s_nop 0
	v_addc_co_u32_e32 v39, vcc, 0, v37, vcc
	global_load_dwordx4 v[140:143], v[36:37], off
	global_load_dwordx4 v[136:139], v[38:39], off
	v_add_co_u32_e32 v38, vcc, s6, v36
	s_waitcnt lgkmcnt(8)
	v_mfma_f32_32x32x16_bf16 v[20:35], v[48:51], v[40:43], v[20:35]
	v_addc_co_u32_e32 v39, vcc, 0, v37, vcc
	v_add_co_u32_e32 v36, vcc, s27, v36
	global_load_dwordx4 v[132:135], v[38:39], off
	s_nop 0
	v_addc_co_u32_e32 v37, vcc, 0, v37, vcc
	global_load_dwordx4 v[128:131], v[36:37], off
	v_or_b32_e32 v36, s26, v151
	v_mad_u32_u24 v145, v36, s33, v152
	ds_read_b128 v[36:39], v145 offset:8704
	ds_read_b128 v[72:75], v145 offset:34816
	ds_read_b128 v[76:79], v145 offset:43520
	ds_read_b128 v[40:43], v145
	ds_read_b128 v[154:157], v145 offset:32
	s_waitcnt lgkmcnt(1)
	v_mfma_f32_32x32x16_bf16 v[52:67], v[68:71], v[40:43], 0
	ds_read_b128 v[158:161], v145 offset:8736
	ds_read_b128 v[162:165], v145 offset:34848
	ds_read_b128 v[166:169], v145 offset:43552
	v_mfma_f32_32x32x16_bf16 v[36:51], v[68:71], v[36:39], 0
	v_mfma_f32_32x32x16_bf16 v[84:99], v[68:71], v[72:75], 0
	v_mfma_f32_32x32x16_bf16 v[68:83], v[68:71], v[76:79], 0
	ds_read_b128 v[172:175], v145 offset:64
	ds_read_b128 v[176:179], v145 offset:8768
	ds_read_b128 v[180:183], v145 offset:34880
	ds_read_b128 v[184:187], v145 offset:43584
	s_waitcnt lgkmcnt(7)
	v_mfma_f32_32x32x16_bf16 v[52:67], v[124:127], v[154:157], v[52:67]
	s_waitcnt lgkmcnt(6)
	v_mfma_f32_32x32x16_bf16 v[36:51], v[124:127], v[158:161], v[36:51]
	s_waitcnt lgkmcnt(5)
	v_mfma_f32_32x32x16_bf16 v[84:99], v[124:127], v[162:165], v[84:99]
	s_waitcnt lgkmcnt(4)
	v_mfma_f32_32x32x16_bf16 v[68:83], v[124:127], v[166:169], v[68:83]
	ds_read_b128 v[154:157], v145 offset:96
	ds_read_b128 v[158:161], v145 offset:8800
	ds_read_b128 v[162:165], v145 offset:34912
	ds_read_b128 v[166:169], v145 offset:43616
	s_waitcnt lgkmcnt(7)
	v_mfma_f32_32x32x16_bf16 v[52:67], v[120:123], v[172:175], v[52:67]
	s_waitcnt lgkmcnt(6)
	v_mfma_f32_32x32x16_bf16 v[36:51], v[120:123], v[176:179], v[36:51]
	s_waitcnt lgkmcnt(5)
; #define RLAS __attribute__((address_space(3)))
; #define RMFMA(a, b, c) __builtin_amdgcn_mfma_f32_32x32x16_bf16(a, b, c, 0, 0, 0)
; __device__ __forceinline__ void out_unit(RLAS unsigned char* L, int b, int h, int c, const bf16_t* QR, bf16_t* PR, const bf16_t* KR, const bf16_t* VR, const bf16_t* GR, const bf16_t* ST, size_t stbatch, const float* gnw, float lgf, float lgb, OutRegs& PF, bool is_first, bool has_next, int nb, int nh ...
;     ...
;       for (int ks = 0; ks < 8; ++ks) {
;           const bf16x8 f0 = *(const RLAS bf16x8*)(R0 + rb0 + 32 * ks), f1 = *(const RLAS bf16x8*)(R0 + rb0 + 32 * RS + 32 * ks), b0 = *(const RLAS bf16x8*)(R1 + rb0 + 32 * ks), b1 = *(const RLAS bf16x8*)(R1 + rb0 + 32 * RS + 32 * ks);
;           Yf[0] = RMFMA(qf[ks], f0, Yf[0]); Yf[1] = RMFMA(qf[ks], f1, Yf[1]); Yb[0] = RMFMA(qf[ks], b0, Yb[0]); Yb[1] = RMFMA(qf[ks], b1, Yb[1]); }
; #pragma unroll
;       for (int q4 = 0; q4 < 4; ++q4) { const int il0 = 32 * ib + 8 * q4 + 4 * h2;
;           const float sf0 = __builtin_amdgcn_exp2f(lgf * (float)(il0 + 1)), sb0 = __builtin_amdgcn_exp2f(lgb * (float)(128 - il0));
; #pragma unroll
;           for (int e = 0; e < 4; ++e) { const float sf = e ? sf0 * __builtin_amdgcn_exp2f(lgf * (float)e) : sf0, sb = e ? sb0 * __builtin_amdgcn_exp2f(-lgb * (float)e) : sb0; const int g = 4 * q4 + e;
; #pragma unroll
;               for (int t = 0; t < 2; ++t) Z[t][g] += sf * Yf[t][g] + sb * Yb[t][g]; } } }
	v_mfma_f32_32x32x16_bf16 v[84:99], v[120:123], v[180:183], v[84:99]
	s_waitcnt lgkmcnt(4)
	v_mfma_f32_32x32x16_bf16 v[68:83], v[120:123], v[184:187], v[68:83]
	ds_read_b128 v[172:175], v145 offset:128
	ds_read_b128 v[176:179], v145 offset:8832
	ds_read_b128 v[180:183], v145 offset:34944
	ds_read_b128 v[184:187], v145 offset:43648
	s_waitcnt lgkmcnt(7)
	v_mfma_f32_32x32x16_bf16 v[52:67], v[116:119], v[154:157], v[52:67]
	s_waitcnt lgkmcnt(6)
	v_mfma_f32_32x32x16_bf16 v[36:51], v[116:119], v[158:161], v[36:51]
	s_waitcnt lgkmcnt(5)
	v_mfma_f32_32x32x16_bf16 v[84:99], v[116:119], v[162:165], v[84:99]
	s_waitcnt lgkmcnt(4)
	v_mfma_f32_32x32x16_bf16 v[68:83], v[116:119], v[166:169], v[68:83]
	ds_read_b128 v[154:157], v145 offset:160
	ds_read_b128 v[158:161], v145 offset:8864
	ds_read_b128 v[162:165], v145 offset:34976
	ds_read_b128 v[166:169], v145 offset:43680
	s_waitcnt lgkmcnt(7)
	v_mfma_f32_32x32x16_bf16 v[52:67], v[112:115], v[172:175], v[52:67]
	s_waitcnt lgkmcnt(6)
	v_mfma_f32_32x32x16_bf16 v[36:51], v[112:115], v[176:179], v[36:51]
	s_waitcnt lgkmcnt(5)
	v_mfma_f32_32x32x16_bf16 v[84:99], v[112:115], v[180:183], v[84:99]
	s_waitcnt lgkmcnt(4)
	v_mfma_f32_32x32x16_bf16 v[68:83], v[112:115], v[184:187], v[68:83]
	ds_read_b128 v[172:175], v145 offset:192
	ds_read_b128 v[176:179], v145 offset:8896
	ds_read_b128 v[180:183], v145 offset:35008
	ds_read_b128 v[184:187], v145 offset:43712
	s_waitcnt lgkmcnt(7)
	v_mfma_f32_32x32x16_bf16 v[52:67], v[108:111], v[154:157], v[52:67]
	s_waitcnt lgkmcnt(6)
	v_mfma_f32_32x32x16_bf16 v[36:51], v[108:111], v[158:161], v[36:51]
	s_waitcnt lgkmcnt(5)
	v_mfma_f32_32x32x16_bf16 v[84:99], v[108:111], v[162:165], v[84:99]
	s_waitcnt lgkmcnt(4)
	v_mfma_f32_32x32x16_bf16 v[68:83], v[108:111], v[166:169], v[68:83]
	ds_read_b128 v[154:157], v145 offset:224
	ds_read_b128 v[158:161], v145 offset:8928
	ds_read_b128 v[162:165], v145 offset:35040
	ds_read_b128 v[166:169], v145 offset:43744
	s_waitcnt lgkmcnt(7)
	v_mfma_f32_32x32x16_bf16 v[52:67], v[104:107], v[172:175], v[52:67]
	s_waitcnt lgkmcnt(6)
	v_mfma_f32_32x32x16_bf16 v[36:51], v[104:107], v[176:179], v[36:51]
	s_waitcnt lgkmcnt(5)
	v_mfma_f32_32x32x16_bf16 v[84:99], v[104:107], v[180:183], v[84:99]
	s_waitcnt lgkmcnt(4)
	v_mfma_f32_32x32x16_bf16 v[68:83], v[104:107], v[184:187], v[68:83]
	s_waitcnt lgkmcnt(0)
	s_barrier
	s_waitcnt lgkmcnt(3)
	v_mfma_f32_32x32x16_bf16 v[52:67], v[100:103], v[154:157], v[52:67]
	s_waitcnt lgkmcnt(2)
	v_mfma_f32_32x32x16_bf16 v[36:51], v[100:103], v[158:161], v[36:51]
	s_waitcnt lgkmcnt(1)
	v_mfma_f32_32x32x16_bf16 v[84:99], v[100:103], v[162:165], v[84:99]
	s_waitcnt lgkmcnt(0)
	v_mfma_f32_32x32x16_bf16 v[68:83], v[100:103], v[166:169], v[68:83]
	v_or_b32_e32 v100, s14, v153
	v_sub_u32_e32 v102, 0x80, v100
	v_or_b32_e32 v101, 1, v100
	v_cvt_f32_i32_e32 v102, v102
	v_cvt_f32_i32_e32 v101, v101
	s_movk_i32 s14, 0x210
	v_mul_f32_e64 v102, -v150, v102
	v_mul_f32_e64 v101, -v149, v101
	v_exp_f32_e32 v102, v102
	v_exp_f32_e32 v101, v101
	v_mul_f32_e32 v84, v102, v84
	v_fmac_f32_e32 v84, v101, v52
	v_mul_f32_e32 v52, v102, v68
	v_exp_f32_e32 v68, v150
	v_fmac_f32_e32 v52, v101, v36
	v_exp_f32_e64 v36, -v149
	v_add_f32_e32 v4, v4, v84
	v_mul_f32_e32 v84, v68, v102
	v_add_f32_e32 v20, v20, v52
	v_mul_f32_e32 v52, v36, v101
	v_mul_f32_e32 v85, v84, v85
	v_fmac_f32_e32 v85, v52, v53
	v_mul_f32_e32 v53, v84, v69
	v_fmac_f32_e32 v53, v52, v37
	v_add_f32_e32 v21, v21, v53
	v_add_f32_e32 v53, v150, v150
	v_mul_f32_e32 v37, -2.0, v149
	v_exp_f32_e32 v53, v53
	v_exp_f32_e32 v37, v37
	v_add_f32_e32 v5, v5, v85
	v_mul_f32_e32 v69, v53, v102
	v_mul_f32_e32 v52, v37, v101
	v_mul_f32_e32 v84, v69, v86
	v_fmac_f32_e32 v84, v52, v54
	v_mul_f32_e32 v54, v69, v70
	v_fmac_f32_e32 v54, v52, v38
	v_add_f32_e32 v22, v22, v54
	v_mul_f32_e32 v54, 0x40400000, v150
	v_mul_f32_e32 v38, 0xc0400000, v149
	v_exp_f32_e32 v54, v54
	v_exp_f32_e32 v38, v38
	v_add_f32_e32 v6, v6, v84
	v_mul_f32_e32 v69, v54, v102
	v_mul_f32_e32 v52, v38, v101
	v_mul_f32_e32 v70, v69, v87
	v_fmac_f32_e32 v70, v52, v55
	v_mul_f32_e32 v55, v69, v71
	v_fmac_f32_e32 v55, v52, v39
	v_sub_u32_e32 v52, 0x78, v100
	v_or_b32_e32 v39, 9, v100
	v_cvt_f32_i32_e32 v52, v52
	v_cvt_f32_i32_e32 v39, v39
	v_add_f32_e32 v23, v23, v55
	v_add_f32_e32 v7, v7, v70
	v_mul_f32_e64 v52, -v150, v52
	v_mul_f32_e64 v39, -v149, v39
	v_exp_f32_e32 v52, v52
	v_exp_f32_e32 v39, v39
	v_mul_f32_e32 v55, v52, v88
	v_fmac_f32_e32 v55, v39, v56
	v_add_f32_e32 v8, v8, v55
	v_mul_f32_e32 v55, v52, v72
	v_fmac_f32_e32 v55, v39, v40
	v_add_f32_e32 v24, v24, v55
	v_mul_f32_e32 v55, v68, v52
	v_mul_f32_e32 v40, v36, v39
	v_mul_f32_e32 v56, v55, v89
	v_mul_f32_e32 v55, v55, v73
	v_fmac_f32_e32 v55, v40, v41
	v_mul_f32_e32 v41, v53, v52
	v_fmac_f32_e32 v56, v40, v57
	v_add_f32_e32 v25, v25, v55
	v_mul_f32_e32 v40, v37, v39
	v_mul_f32_e32 v55, v41, v90
	v_mul_f32_e32 v41, v41, v74
	v_fmac_f32_e32 v55, v40, v58
	v_fmac_f32_e32 v41, v40, v42
	v_mul_f32_e32 v40, v54, v52
	v_add_f32_e32 v26, v26, v41
	v_mul_f32_e32 v39, v38, v39
	v_mul_f32_e32 v41, v40, v91
	v_mul_f32_e32 v40, v40, v75
	v_fmac_f32_e32 v40, v39, v43
	v_add_f32_e32 v27, v27, v40
	v_sub_u32_e32 v40, 0x70, v100
	v_fmac_f32_e32 v41, v39, v59
	v_or_b32_e32 v39, 17, v100
	v_cvt_f32_i32_e32 v40, v40
	v_cvt_f32_i32_e32 v39, v39
	v_add_f32_e32 v11, v11, v41
	v_add_f32_e32 v9, v9, v56
	v_mul_f32_e64 v40, -v150, v40
	v_mul_f32_e64 v39, -v149, v39
	v_exp_f32_e32 v40, v40
	v_exp_f32_e32 v39, v39
	v_add_f32_e32 v10, v10, v55
	v_mul_f32_e32 v41, v40, v92
	v_fmac_f32_e32 v41, v39, v60
	v_add_f32_e32 v12, v12, v41
	v_mul_f32_e32 v41, v40, v76
	v_fmac_f32_e32 v41, v39, v44
; __device__ __forceinline__ int crow(int r,int hi){return (r&3)+8*(r>>2)+4*hi;}
; #define RLAS __attribute__((address_space(3)))
; __device__ __forceinline__ int crow(int g, int hi) { return (g & 3) + 8 * (g >> 2) + 4 * hi; }
; __device__ __forceinline__ void out_prefetch(OutRegs& R, int b, int h, int c, const bf16_t* QR, const bf16_t* KR, const bf16_t* VR) {
;     int tid_ = threadIdx.x; asm volatile("" : "+v"(tid_));
;     const int grow = (tid_ >> 6) * 16 + ((tid_ >> 4) & 3), gch = tid_ & 15; const size_t tok0 = (size_t)b * SEQ + (size_t)c * 128;
;     const bf16_t* kp = KR + (tok0 + grow) * 512 + h * 128 + gch * 8; const bf16_t* vp = VR + (tok0 + grow) * 512 + h * 128 + gch * 8; const bf16_t* qp = QR + (tok0 + grow) * QRP + h * 128 + gch * 8;
; #pragma unroll
;     for (int i = 0; i < 4; ++i) { R.q[i] = *(const u32x4*)(qp + (size_t)(4 * i) * QRP); R.k[i] = *(const u32x4*)(kp + (size_t)(4 * i) * 512); R.v[i] = *(const u32x4*)(vp + (size_t)(4 * i) * 512); }
; __device__ __forceinline__ void out_unit(RLAS unsigned char* L, int b, int h, int c, const bf16_t* QR, bf16_t* PR, const bf16_t* KR, const bf16_t* VR, const bf16_t* GR, const bf16_t* ST, size_t stbatch, const float* gnw, float lgf, float lgb, OutRegs& PF, bool is_first, bool has_next, int nb, int nh ...
;     ...
;     LBAR();
;     { RLAS float* Os = (RLAS float*)L;
; #pragma unroll
;       for (int t = 0; t < 2; ++t)
; #pragma unroll
;           for (int g = 0; g < 16; ++g) Os[(32 * ib + crow(g, h2)) * OS + 64 * dvh + 32 * t + r] = Z[t][g]; }
;     LBAR();
;     asm volatile("" ::: "memory"); __builtin_amdgcn_sched_barrier(0);
;     f32x4 w0 = *(const f32x4*)(gnw + h * 128 + gch * 8), w1 = *(const f32x4*)(gnw + h * 128 + gch * 8 + 4);
;     asm volatile("" : "+v"(w0), "+v"(w1));
;     out_prefetch(PF, has_next ? nb : b, has_next ? nh : h, has_next ? nc : c, QR, KR, VR);
;     { const int cb = h * 128 + gch * 8;
;       f32x4 o[4][2]; float sm[4], vq[4];
; #pragma unroll
;       for (int i = 0; i < 4; ++i) { const RLAS float* Os = (const RLAS float*)L + (grow + 4 * i) * OS + gch * 8; o[i][0] = *(const RLAS f32x4*)Os; o[i][1] = *(const RLAS f32x4*)(Os + 4);
;           sm[i] = ((o[i][0][0] + o[i][0][1]) + (o[i][0][2] + o[i][0][3])) + ((o[i][1][0] + o[i][1][1]) + (o[i][1][2] + o[i][1][3])); }
	v_mul_f32_e32 v42, v68, v40
	v_add_f32_e32 v28, v28, v41
	v_mul_f32_e32 v41, v36, v39
	v_mul_f32_e32 v43, v42, v93
	v_mul_f32_e32 v42, v42, v77
	v_fmac_f32_e32 v42, v41, v45
	v_fmac_f32_e32 v43, v41, v61
	v_add_f32_e32 v29, v29, v42
	v_mul_f32_e32 v42, v53, v40
	v_add_f32_e32 v13, v13, v43
	v_mul_f32_e32 v41, v37, v39
	v_mul_f32_e32 v43, v42, v94
	v_mul_f32_e32 v42, v42, v78
	v_mul_f32_e32 v40, v54, v40
	v_fmac_f32_e32 v43, v41, v62
	v_fmac_f32_e32 v42, v41, v46
	v_mul_f32_e32 v39, v38, v39
	v_mul_f32_e32 v41, v40, v95
	v_mul_f32_e32 v40, v40, v79
	v_fmac_f32_e32 v40, v39, v47
	v_add_f32_e32 v31, v31, v40
	v_sub_u32_e32 v40, 0x68, v100
	v_fmac_f32_e32 v41, v39, v63
	v_or_b32_e32 v39, 25, v100
	v_cvt_f32_i32_e32 v40, v40
	v_cvt_f32_i32_e32 v39, v39
	v_add_f32_e32 v15, v15, v41
	v_add_f32_e32 v30, v30, v42
	v_mul_f32_e64 v40, -v150, v40
	v_mul_f32_e64 v39, -v149, v39
	v_exp_f32_e32 v40, v40
	v_exp_f32_e32 v39, v39
	v_add_f32_e32 v14, v14, v43
	v_mul_f32_e32 v41, v40, v96
	v_fmac_f32_e32 v41, v39, v64
	v_add_f32_e32 v16, v16, v41
	v_mul_f32_e32 v41, v40, v80
	v_fmac_f32_e32 v41, v39, v48
	v_add_f32_e32 v32, v32, v41
	v_mul_f32_e32 v41, v68, v40
	v_mul_f32_e32 v36, v36, v39
	v_mul_f32_e32 v42, v41, v97
	v_mul_f32_e32 v41, v41, v81
	v_fmac_f32_e32 v42, v36, v65
	v_fmac_f32_e32 v41, v36, v49
	v_mul_f32_e32 v36, v37, v39
	v_mul_f32_e32 v37, v53, v40
	v_add_f32_e32 v33, v33, v41
	v_mul_f32_e32 v41, v37, v98
	v_mul_f32_e32 v37, v37, v82
	v_fmac_f32_e32 v37, v36, v50
	v_add_f32_e32 v34, v34, v37
	v_mul_f32_e32 v37, v54, v40
	v_fmac_f32_e32 v41, v36, v66
	v_mul_f32_e32 v36, v38, v39
	v_mul_f32_e32 v38, v37, v99
	v_mul_f32_e32 v37, v37, v83
	v_fmac_f32_e32 v37, v36, v51
	v_fmac_f32_e32 v38, v36, v67
	v_add_f32_e32 v35, v35, v37
	v_lshlrev_b32_e32 v36, 2, v151
	v_mul_lo_u32 v37, v100, s14
	v_add3_u32 v36, s1, v36, v37
	ds_write2_b32 v36, v4, v20 offset1:32
	ds_write2_b32 v36, v5, v21 offset0:132 offset1:164
	v_add_u32_e32 v4, 0x400, v36
	ds_write2_b32 v4, v6, v22 offset0:8 offset1:40
	ds_write2_b32 v4, v7, v23 offset0:140 offset1:172
	v_add_u32_e32 v4, 0x1000, v36
	ds_write2_b32 v4, v8, v24 offset0:32 offset1:64
	ds_write2_b32 v4, v9, v25 offset0:164 offset1:196
	v_add_u32_e32 v4, 0x1400, v36
	ds_write2_b32 v4, v10, v26 offset0:40 offset1:72
	ds_write2_b32 v4, v11, v27 offset0:172 offset1:204
	v_add_u32_e32 v4, 0x2000, v36
	ds_write2_b32 v4, v12, v28 offset0:64 offset1:96
	ds_write2_b32 v4, v13, v29 offset0:196 offset1:228
	v_add_u32_e32 v4, 0x2400, v36
	ds_write2_b32 v4, v14, v30 offset0:72 offset1:104
	ds_write2_b32 v4, v15, v31 offset0:204 offset1:236
	v_add_u32_e32 v4, 0x3000, v36
	v_add_f32_e32 v17, v17, v42
	ds_write2_b32 v4, v16, v32 offset0:96 offset1:128
	v_add_u32_e32 v4, 0x3200, v36
	v_add_f32_e32 v18, v18, v41
	ds_write2_b32 v4, v17, v33 offset0:100 offset1:132
	v_add_u32_e32 v4, 0x3400, v36
	v_add_f32_e32 v19, v19, v38
	ds_write2_b32 v4, v18, v34 offset0:104 offset1:136
	v_add_u32_e32 v4, 0x3600, v36
	ds_write2_b32 v4, v19, v35 offset0:108 offset1:140
	s_waitcnt lgkmcnt(0)
	s_barrier
	v_lshlrev_b32_e32 v60, 5, v148
	global_load_dwordx4 v[52:55], v60, s[4:5] offset:16
	global_load_dwordx4 v[56:59], v60, s[4:5]
	s_cselect_b32 s0, s21, s0
	v_mov_b32_e32 v10, v0
	s_cselect_b32 s4, s22, s15
	s_cselect_b32 s5, s23, s20
	s_ashr_i32 s1, s0, 31
	s_lshl_b64 s[0:1], s[0:1], 12
	s_lshl_b32 s5, s5, 7
	s_or_b32 s0, s0, s5
	v_mov_b32_e32 v11, v3
	v_mul_lo_u32 v61, v144, s14
	v_add3_u32 v92, 0, v60, v61
	v_or_b32_e32 v2, s16, v2
	s_add_i32 s12, s12, 1
	s_add_i32 s13, s13, s3
	s_waitcnt vmcnt(0)
	s_nop 0
	v_ashrrev_i32_e32 v4, 2, v10
	v_bfe_u32 v5, v10, 4, 2
	v_and_or_b32 v4, v4, -16, v5
	v_ashrrev_i32_e32 v5, 31, v4
	v_lshl_add_u64 v[4:5], s[0:1], 0, v[4:5]
	v_lshlrev_b64 v[6:7], 10, v[4:5]
	v_lshlrev_b64 v[4:5], 11, v[4:5]
	s_lshl_b32 s0, s4, 8
	s_mov_b32 s1, s17
	v_lshlrev_b32_e32 v10, 4, v10
	v_lshl_add_u64 v[4:5], s[82:83], 0, v[4:5]
	v_and_b32_e32 v10, 0xf0, v10
	v_lshl_add_u64 v[4:5], v[4:5], 0, s[0:1]
	v_lshl_add_u64 v[8:9], s[92:93], 0, v[6:7]
	v_readlane_b32 s4, v252, 30
	v_lshl_add_u64 v[24:25], v[4:5], 0, v[10:11]
	v_lshl_add_u64 v[8:9], v[8:9], 0, s[0:1]
	v_readlane_b32 s5, v252, 31
	v_add_co_u32_e32 v12, vcc, s7, v24
	v_lshl_add_u64 v[44:45], v[8:9], 0, v[10:11]
	v_lshl_add_u64 v[6:7], s[4:5], 0, v[6:7]
	v_addc_co_u32_e32 v13, vcc, 0, v25, vcc
	v_lshl_add_u64 v[6:7], v[6:7], 0, s[0:1]
	v_add_co_u32_e32 v26, vcc, s7, v44
	v_lshl_add_u64 v[46:47], v[6:7], 0, v[10:11]
	s_nop 0
	v_addc_co_u32_e32 v27, vcc, 0, v45, vcc
	v_add_co_u32_e32 v36, vcc, s7, v46
	global_load_dwordx4 v[16:19], v[24:25], off
	global_load_dwordx4 v[4:7], v[44:45], off
	global_load_dwordx4 v[8:11], v[46:47], off
	v_addc_co_u32_e32 v37, vcc, 0, v47, vcc
	v_add_co_u32_e32 v32, vcc, s6, v24
	s_movk_i32 s0, 0x3000
	s_nop 0
	v_addc_co_u32_e32 v33, vcc, 0, v25, vcc
	v_add_co_u32_e32 v24, vcc, s27, v24
	global_load_dwordx4 v[12:15], v[12:13], off
	s_nop 0
	v_addc_co_u32_e32 v25, vcc, 0, v25, vcc
	v_add_co_u32_e32 v44, vcc, s0, v44
	global_load_dwordx4 v[20:23], v[26:27], off offset:-4096
	s_nop 0
	v_addc_co_u32_e32 v45, vcc, 0, v45, vcc
	global_load_dwordx4 v[28:31], v[36:37], off offset:-4096
	global_load_dwordx4 v[40:43], v[32:33], off
	s_nop 0
	global_load_dwordx4 v[32:35], v[26:27], off
	s_nop 0
	global_load_dwordx4 v[36:39], v[36:37], off
	s_nop 0
	global_load_dwordx4 v[24:27], v[24:25], off
	s_nop 0
	global_load_dwordx4 v[48:51], v[44:45], off
	v_add_co_u32_e32 v44, vcc, s0, v46
	s_mov_b32 s0, 0x358637bd
	s_nop 0
	v_addc_co_u32_e32 v45, vcc, 0, v47, vcc
	global_load_dwordx4 v[44:47], v[44:45], off
	ds_read_b128 v[80:83], v92
	ds_read_b128 v[76:79], v92 offset:16
	ds_read_b128 v[88:91], v92 offset:2112
	ds_read_b128 v[84:87], v92 offset:2128
	ds_read_b128 v[72:75], v92 offset:4224
	ds_read_b128 v[68:71], v92 offset:4240
	s_waitcnt lgkmcnt(5)
; #define RLAS __attribute__((address_space(3)))
; __device__ __forceinline__ void out_unit(RLAS unsigned char* L, int b, int h, int c, const bf16_t* QR, bf16_t* PR, const bf16_t* KR, const bf16_t* VR, const bf16_t* GR, const bf16_t* ST, size_t stbatch, const float* gnw, float lgf, float lgb, OutRegs& PF, bool is_first, bool has_next, int nb, int nh ...
;     ...
;       for (int i = 0; i < 4; ++i) { const RLAS float* Os = (const RLAS float*)L + (grow + 4 * i) * OS + gch * 8; o[i][0] = *(const RLAS f32x4*)Os; o[i][1] = *(const RLAS f32x4*)(Os + 4);
;           sm[i] = ((o[i][0][0] + o[i][0][1]) + (o[i][0][2] + o[i][0][3])) + ((o[i][1][0] + o[i][1][1]) + (o[i][1][2] + o[i][1][3])); }
; #pragma unroll
;       for (int i = 0; i < 4; ++i) sm[i] = row16_sum(sm[i]);
; #pragma unroll
;       for (int i = 0; i < 4; ++i) { const float mean = sm[i] * (1.f / 128.f); o[i][0] = o[i][0] - mean; o[i][1] = o[i][1] - mean;
;           vq[i] = ((o[i][0][0] * o[i][0][0] + o[i][0][1] * o[i][0][1]) + (o[i][0][2] * o[i][0][2] + o[i][0][3] * o[i][0][3])) + ((o[i][1][0] * o[i][1][0] + o[i][1][1] * o[i][1][1]) + (o[i][1][2] * o[i][1][2] + o[i][1][3] * o[i][1][3])); }
; #pragma unroll
;       for (int i = 0; i < 4; ++i) vq[i] = row16_sum(vq[i]);
	v_mov_b32_e32 v60, v80
	s_waitcnt lgkmcnt(4)
	v_mov_b32_e32 v61, v76
	v_mov_b32_e32 v62, v81
	v_mov_b32_e32 v63, v77
	v_pk_add_f32 v[60:61], v[60:61], v[62:63]
	v_mov_b32_e32 v62, v82
	v_mov_b32_e32 v63, v78
	v_mov_b32_e32 v64, v83
	v_mov_b32_e32 v65, v79
	v_pk_add_f32 v[62:63], v[62:63], v[64:65]
	s_waitcnt lgkmcnt(3)
	v_mov_b32_e32 v64, v91
	v_pk_add_f32 v[60:61], v[60:61], v[62:63]
	v_mov_b32_e32 v62, v89
	v_add_f32_e32 v98, v60, v61
	v_mov_b32_e32 v60, v88
	s_waitcnt lgkmcnt(2)
	v_mov_b32_e32 v61, v84
	v_mov_b32_e32 v63, v85
	v_pk_add_f32 v[60:61], v[60:61], v[62:63]
	v_mov_b32_e32 v62, v90
	v_mov_b32_e32 v63, v86
	v_mov_b32_e32 v65, v87
	v_pk_add_f32 v[62:63], v[62:63], v[64:65]
	s_waitcnt lgkmcnt(1)
	v_mov_b32_e32 v64, v75
	v_pk_add_f32 v[60:61], v[60:61], v[62:63]
	v_mov_b32_e32 v62, v73
	v_add_f32_e32 v99, v60, v61
	v_mov_b32_e32 v60, v72
	s_waitcnt lgkmcnt(0)
	v_mov_b32_e32 v61, v68
	v_mov_b32_e32 v63, v69
	v_pk_add_f32 v[60:61], v[60:61], v[62:63]
	v_mov_b32_e32 v62, v74
	v_mov_b32_e32 v63, v70
	v_mov_b32_e32 v65, v71
	v_pk_add_f32 v[62:63], v[62:63], v[64:65]
	s_nop 0
	v_pk_add_f32 v[60:61], v[60:61], v[62:63]
	s_nop 0
	v_add_f32_e32 v100, v60, v61
	ds_read_b128 v[64:67], v92 offset:6336
	ds_read_b128 v[60:63], v92 offset:6352
	s_waitcnt lgkmcnt(1)
	v_mov_b32_e32 v92, v64
	s_waitcnt lgkmcnt(0)
	v_mov_b32_e32 v93, v60
	v_mov_b32_e32 v94, v65
	v_mov_b32_e32 v95, v61
	v_pk_add_f32 v[92:93], v[92:93], v[94:95]
	v_mov_b32_e32 v94, v66
	v_mov_b32_e32 v95, v62
	v_mov_b32_e32 v96, v67
	v_mov_b32_e32 v97, v63
	v_pk_add_f32 v[94:95], v[94:95], v[96:97]
	s_nop 0
	v_pk_add_f32 v[92:93], v[92:93], v[94:95]
	v_add_f32_dpp v94, v99, v99 quad_perm:[1,0,3,2] row_mask:0xf bank_mask:0xf bound_ctrl:1
	v_add_f32_e32 v92, v92, v93
	v_add_f32_dpp v93, v98, v98 quad_perm:[1,0,3,2] row_mask:0xf bank_mask:0xf bound_ctrl:1
	v_add_f32_dpp v94, v94, v94 quad_perm:[2,3,0,1] row_mask:0xf bank_mask:0xf bound_ctrl:1
	v_add_f32_dpp v92, v92, v92 quad_perm:[1,0,3,2] row_mask:0xf bank_mask:0xf bound_ctrl:1
	v_add_f32_dpp v93, v93, v93 quad_perm:[2,3,0,1] row_mask:0xf bank_mask:0xf bound_ctrl:1
	v_add_f32_dpp v94, v94, v94 row_half_mirror row_mask:0xf bank_mask:0xf bound_ctrl:1
	v_add_f32_dpp v92, v92, v92 quad_perm:[2,3,0,1] row_mask:0xf bank_mask:0xf bound_ctrl:1
	v_add_f32_dpp v93, v93, v93 row_half_mirror row_mask:0xf bank_mask:0xf bound_ctrl:1
	v_add_f32_dpp v102, v94, v94 row_mirror row_mask:0xf bank_mask:0xf bound_ctrl:1
	v_add_f32_dpp v92, v92, v92 row_half_mirror row_mask:0xf bank_mask:0xf bound_ctrl:1
	v_add_f32_dpp v93, v93, v93 row_mirror row_mask:0xf bank_mask:0xf bound_ctrl:1
	v_fmamk_f32 v81, v93, 0xbc000000, v81
	v_fmamk_f32 v77, v93, 0xbc000000, v77
	v_fmamk_f32 v99, v93, 0xbc000000, v83
	v_fmamk_f32 v98, v93, 0xbc000000, v82
	v_fmac_f32_e32 v80, 0xbc000000, v93
	v_fmamk_f32 v97, v93, 0xbc000000, v79
	v_fmac_f32_e32 v76, 0xbc000000, v93
	v_mov_b32_e32 v82, v81
	v_mov_b32_e32 v83, v77
	v_add_f32_dpp v104, v92, v92 row_mirror row_mask:0xf bank_mask:0xf bound_ctrl:1
	v_fmamk_f32 v96, v93, 0xbc000000, v78
	v_mov_b32_e32 v78, v80
	v_mov_b32_e32 v79, v76
	v_pk_mul_f32 v[82:83], v[82:83], v[82:83]
	v_mov_b32_e32 v92, v99
	v_mov_b32_e32 v93, v97
	v_add_f32_dpp v94, v100, v100 quad_perm:[1,0,3,2] row_mask:0xf bank_mask:0xf bound_ctrl:1
	v_pk_fma_f32 v[78:79], v[78:79], v[78:79], v[82:83]
	v_mov_b32_e32 v82, v98
	v_mov_b32_e32 v83, v96
	v_pk_mul_f32 v[92:93], v[92:93], v[92:93]
	v_add_f32_dpp v94, v94, v94 quad_perm:[2,3,0,1] row_mask:0xf bank_mask:0xf bound_ctrl:1
	v_pk_fma_f32 v[82:83], v[82:83], v[82:83], v[92:93]
	v_fmamk_f32 v89, v102, 0xbc000000, v89
	v_fmamk_f32 v85, v102, 0xbc000000, v85
	v_add_f32_dpp v94, v94, v94 row_half_mirror row_mask:0xf bank_mask:0xf bound_ctrl:1
	v_pk_add_f32 v[100:101], v[78:79], v[82:83]
	v_fmamk_f32 v93, v102, 0xbc000000, v91
	v_fmac_f32_e32 v88, 0xbc000000, v102
	v_fmamk_f32 v95, v102, 0xbc000000, v87
	v_fmac_f32_e32 v84, 0xbc000000, v102
	v_mov_b32_e32 v82, v89
	v_mov_b32_e32 v83, v85
	v_add_f32_dpp v103, v94, v94 row_mirror row_mask:0xf bank_mask:0xf bound_ctrl:1
	v_fmamk_f32 v92, v102, 0xbc000000, v90
	v_fmamk_f32 v94, v102, 0xbc000000, v86
	v_mov_b32_e32 v78, v88
	v_mov_b32_e32 v79, v84
	v_pk_mul_f32 v[82:83], v[82:83], v[82:83]
	v_mov_b32_e32 v86, v93
	v_mov_b32_e32 v87, v95
	v_pk_fma_f32 v[78:79], v[78:79], v[78:79], v[82:83]
	v_mov_b32_e32 v82, v92
	v_mov_b32_e32 v83, v94
	v_pk_mul_f32 v[86:87], v[86:87], v[86:87]
	v_fmamk_f32 v73, v103, 0xbc000000, v73
	v_pk_fma_f32 v[82:83], v[82:83], v[82:83], v[86:87]
	v_fmamk_f32 v69, v103, 0xbc000000, v69
	v_pk_add_f32 v[90:91], v[78:79], v[82:83]
	v_fmamk_f32 v75, v103, 0xbc000000, v75
	v_fmac_f32_e32 v72, 0xbc000000, v103
	v_fmamk_f32 v79, v103, 0xbc000000, v71
	v_fmac_f32_e32 v68, 0xbc000000, v103
	v_mov_b32_e32 v82, v73
	v_mov_b32_e32 v83, v69
	v_fmamk_f32 v74, v103, 0xbc000000, v74
	v_fmamk_f32 v78, v103, 0xbc000000, v70
	v_mov_b32_e32 v70, v72
	v_mov_b32_e32 v71, v68
	v_pk_mul_f32 v[82:83], v[82:83], v[82:83]
	v_mov_b32_e32 v86, v75
	v_mov_b32_e32 v87, v79
	v_pk_fma_f32 v[70:71], v[70:71], v[70:71], v[82:83]
	v_mov_b32_e32 v82, v74
	v_mov_b32_e32 v83, v78
	v_pk_mul_f32 v[86:87], v[86:87], v[86:87]
	v_fmamk_f32 v65, v104, 0xbc000000, v65
	v_pk_fma_f32 v[82:83], v[82:83], v[82:83], v[86:87]
	v_fmamk_f32 v61, v104, 0xbc000000, v61
	v_pk_add_f32 v[82:83], v[70:71], v[82:83]
	v_fmamk_f32 v67, v104, 0xbc000000, v67
	v_fmac_f32_e32 v64, 0xbc000000, v104
	v_fmamk_f32 v71, v104, 0xbc000000, v63
	v_fmac_f32_e32 v60, 0xbc000000, v104
	v_mov_b32_e32 v86, v65
	v_mov_b32_e32 v87, v61
	v_fmamk_f32 v66, v104, 0xbc000000, v66
	v_fmamk_f32 v70, v104, 0xbc000000, v62
	v_mov_b32_e32 v62, v64
;       #define SILU_(x) ((x)*__builtin_amdgcn_rcpf(1.f+__builtin_amdgcn_exp2f(-1.4426950408889634f*(x))))
; __device__ __forceinline__ unsigned pkbf(float lo, float hi) { const f32x2r v = {lo, hi}; return __builtin_bit_cast(unsigned, __builtin_convertvector(v, bf16x2r)); }
; #define SILU_(x) ((x) * __builtin_amdgcn_rcpf(1.f + __builtin_amdgcn_exp2f(-1.4426950408889634f * (x))))
; __device__ __forceinline__ void out_unit(RLAS unsigned char* L, int b, int h, int c, const bf16_t* QR, bf16_t* PR, const bf16_t* KR, const bf16_t* VR, const bf16_t* GR, const bf16_t* ST, size_t stbatch, const float* gnw, float lgf, float lgb, OutRegs& PF, bool is_first, bool has_next, int nb, int nh ...
;     ...
;       for (int i = 0; i < 4; ++i) { const float mean = sm[i] * (1.f / 128.f); o[i][0] = o[i][0] - mean; o[i][1] = o[i][1] - mean;
;           vq[i] = ((o[i][0][0] * o[i][0][0] + o[i][0][1] * o[i][0][1]) + (o[i][0][2] * o[i][0][2] + o[i][0][3] * o[i][0][3])) + ((o[i][1][0] * o[i][1][0] + o[i][1][1] * o[i][1][1]) + (o[i][1][2] * o[i][1][2] + o[i][1][3] * o[i][1][3])); }
; #pragma unroll
;       for (int i = 0; i < 4; ++i) vq[i] = row16_sum(vq[i]);
;       bf16_t* op = PR + (tok0 + grow) * QRP + cb;
; #pragma unroll
;       for (int i = 0; i < 4; ++i) { const float rstd = rsqrtf(vq[i] * (1.f / 128.f) + EPS); const u32x4 gw = gwr[i];
;           const f32x4 a0 = o[i][0] * rstd * w0, a1 = o[i][1] * rstd * w1; u32x4 ow;
;     ...
;           const float g0 = __uint_as_float(gw.x << 16), g1 = __uint_as_float(gw.x & 0xffff0000u), g2 = __uint_as_float(gw.y << 16), g3 = __uint_as_float(gw.y & 0xffff0000u), g4 = __uint_as_float(gw.z << 16), g5 = __uint_as_float(gw.z & 0xffff0000u), g6 = __uint_as_float(gw.w << 16), g7 = __uint_as_float(gw.w & 0xffff0000u);
;           ow.x = pkbf(a0[0] * SILU_(g0), a0[1] * SILU_(g1)); ow.y = pkbf(a0[2] * SILU_(g2), a0[3] * SILU_(g3));
;           ow.z = pkbf(a1[0] * SILU_(g4), a1[1] * SILU_(g5)); ow.w = pkbf(a1[2] * SILU_(g6), a1[3] * SILU_(g7));
;     ...
;           *(u32x4*)(op + (size_t)(4 * i) * QRP) = ow; } }
	v_mov_b32_e32 v63, v60
	v_pk_mul_f32 v[86:87], v[86:87], v[86:87]
	v_mov_b32_e32 v102, v67
	v_mov_b32_e32 v103, v71
	v_pk_fma_f32 v[62:63], v[62:63], v[62:63], v[86:87]
	v_mov_b32_e32 v86, v66
	v_mov_b32_e32 v87, v70
	v_pk_mul_f32 v[102:103], v[102:103], v[102:103]
	s_nop 0
	v_pk_fma_f32 v[86:87], v[86:87], v[86:87], v[102:103]
	v_lshlrev_b32_e32 v102, 16, v140
	v_pk_add_f32 v[86:87], v[62:63], v[86:87]
	v_lshl_add_u64 v[62:63], s[82:83], 0, v[146:147]
	v_lshl_add_u64 v[62:63], v[62:63], 0, v[2:3]
	v_mul_f32_e32 v2, 0xbfb8aa3b, v102
	v_exp_f32_e32 v2, v2
	v_and_b32_e32 v103, 0xffff0000, v140
	v_add_f32_e32 v2, 1.0, v2
	v_rcp_f32_e32 v104, v2
	v_mul_f32_e32 v2, 0xbfb8aa3b, v103
	v_exp_f32_e32 v2, v2
	s_nop 0
	v_add_f32_e32 v2, 1.0, v2
	v_rcp_f32_e32 v105, v2
	s_nop 0
	v_pk_mul_f32 v[102:103], v[104:105], v[102:103]
	v_lshlrev_b32_e32 v104, 16, v141
	v_mul_f32_e32 v2, 0xbfb8aa3b, v104
	v_exp_f32_e32 v2, v2
	v_and_b32_e32 v105, 0xffff0000, v141
	v_add_f32_e32 v2, 1.0, v2
	v_rcp_f32_e32 v106, v2
	v_mul_f32_e32 v2, 0xbfb8aa3b, v105
	v_exp_f32_e32 v2, v2
	s_nop 0
	v_add_f32_e32 v2, 1.0, v2
	v_rcp_f32_e32 v107, v2
	s_nop 0
	v_pk_mul_f32 v[104:105], v[106:107], v[104:105]
	v_lshlrev_b32_e32 v106, 16, v142
	v_mul_f32_e32 v2, 0xbfb8aa3b, v106
	v_exp_f32_e32 v2, v2
	v_and_b32_e32 v107, 0xffff0000, v142
	v_add_f32_e32 v2, 1.0, v2
	v_rcp_f32_e32 v108, v2
	v_mul_f32_e32 v2, 0xbfb8aa3b, v107
	v_exp_f32_e32 v2, v2
	s_nop 0
	v_add_f32_e32 v2, 1.0, v2
	v_rcp_f32_e32 v109, v2
	s_nop 0
	v_pk_mul_f32 v[106:107], v[108:109], v[106:107]
	v_lshlrev_b32_e32 v108, 16, v143
	v_mul_f32_e32 v2, 0xbfb8aa3b, v108
	v_exp_f32_e32 v2, v2
	v_and_b32_e32 v109, 0xffff0000, v143
	v_add_f32_e32 v2, 1.0, v2
	v_rcp_f32_e32 v110, v2
	v_mul_f32_e32 v2, 0xbfb8aa3b, v109
	v_exp_f32_e32 v2, v2
	s_nop 0
	v_add_f32_e32 v2, 1.0, v2
	v_rcp_f32_e32 v111, v2
	s_nop 0
	v_pk_mul_f32 v[108:109], v[110:111], v[108:109]
	v_mov_b32_e32 v110, v90
	v_mov_b32_e32 v111, v100
	v_mov_b32_e32 v100, v91
	v_pk_add_f32 v[90:91], v[110:111], v[100:101]
	s_nop 1
	v_mov_b32_dpp v101, v91 quad_perm:[1,0,3,2] row_mask:0xf bank_mask:0xf bound_ctrl:1
	v_mov_b32_dpp v100, v90 quad_perm:[1,0,3,2] row_mask:0xf bank_mask:0xf bound_ctrl:1
	v_pk_add_f32 v[90:91], v[90:91], v[100:101]
	s_nop 1
	v_mov_b32_dpp v101, v91 quad_perm:[2,3,0,1] row_mask:0xf bank_mask:0xf bound_ctrl:1
	v_mov_b32_dpp v100, v90 quad_perm:[2,3,0,1] row_mask:0xf bank_mask:0xf bound_ctrl:1
	v_pk_add_f32 v[90:91], v[90:91], v[100:101]
	s_nop 1
	v_mov_b32_dpp v101, v91 row_half_mirror row_mask:0xf bank_mask:0xf bound_ctrl:1
	v_mov_b32_dpp v100, v90 row_half_mirror row_mask:0xf bank_mask:0xf bound_ctrl:1
	v_pk_add_f32 v[90:91], v[90:91], v[100:101]
	s_nop 1
	v_mov_b32_dpp v101, v91 row_mirror row_mask:0xf bank_mask:0xf bound_ctrl:1
	v_mov_b32_dpp v100, v90 row_mirror row_mask:0xf bank_mask:0xf bound_ctrl:1
	v_pk_add_f32 v[100:101], v[90:91], v[100:101]
	v_mov_b64_e32 v[90:91], s[0:1]
	s_brev_b32 s0, 60
	v_pk_fma_f32 v[100:101], v[100:101], s[0:1], v[90:91] op_sel_hi:[1,0,0]
	s_nop 0
	v_mul_f32_e32 v2, 0x4b800000, v101
	v_cmp_gt_f32_e64 s[38:39], s35, v101
	v_cmp_gt_f32_e32 vcc, s35, v100
	s_nop 0
	v_cndmask_b32_e64 v2, v101, v2, s[38:39]
	v_rsq_f32_e32 v2, v2
	s_nop 0
	v_mul_f32_e32 v101, 0x45800000, v2
	v_cndmask_b32_e64 v2, v2, v101, s[38:39]
	v_pk_mul_f32 v[80:81], v[80:81], v[2:3] op_sel_hi:[1,0]
	v_pk_mul_f32 v[98:99], v[98:99], v[2:3] op_sel_hi:[1,0]
	v_pk_mul_f32 v[76:77], v[76:77], v[2:3] op_sel_hi:[1,0]
	v_pk_mul_f32 v[96:97], v[96:97], v[2:3] op_sel_hi:[1,0]
	v_mul_f32_e32 v2, 0x4b800000, v100
	v_cndmask_b32_e32 v2, v100, v2, vcc
	v_rsq_f32_e32 v2, v2
	v_pk_mul_f32 v[80:81], v[56:57], v[80:81]
	v_pk_mul_f32 v[76:77], v[52:53], v[76:77]
	v_pk_mul_f32 v[98:99], v[58:59], v[98:99]
	v_pk_mul_f32 v[110:111], v[54:55], v[96:97]
	v_pk_mul_f32 v[80:81], v[102:103], v[80:81]
	v_pk_mul_f32 v[76:77], v[106:107], v[76:77]
	v_cvt_pk_bf16_f32 v96, v80, v81
	v_pk_mul_f32 v[80:81], v[104:105], v[98:99]
	v_cvt_pk_bf16_f32 v98, v76, v77
	v_pk_mul_f32 v[76:77], v[108:109], v[110:111]
	v_cvt_pk_bf16_f32 v97, v80, v81
	v_cvt_pk_bf16_f32 v99, v76, v77
	v_mul_f32_e32 v76, 0x45800000, v2
	v_cndmask_b32_e32 v2, v2, v76, vcc
	v_pk_mul_f32 v[80:81], v[92:93], v[2:3] op_sel_hi:[1,0]
	v_lshlrev_b32_e32 v92, 16, v136
	v_pk_mul_f32 v[76:77], v[88:89], v[2:3] op_sel_hi:[1,0]
	v_pk_mul_f32 v[84:85], v[84:85], v[2:3] op_sel_hi:[1,0]
	v_pk_mul_f32 v[88:89], v[94:95], v[2:3] op_sel_hi:[1,0]
	v_mul_f32_e32 v2, 0xbfb8aa3b, v92
	v_exp_f32_e32 v2, v2
	v_and_b32_e32 v93, 0xffff0000, v136
	v_pk_mul_f32 v[76:77], v[56:57], v[76:77]
	v_pk_mul_f32 v[80:81], v[58:59], v[80:81]
	v_add_f32_e32 v2, 1.0, v2
	v_rcp_f32_e32 v94, v2
	v_mul_f32_e32 v2, 0xbfb8aa3b, v93
	v_exp_f32_e32 v2, v2
	v_pk_mul_f32 v[84:85], v[52:53], v[84:85]
	v_pk_mul_f32 v[88:89], v[54:55], v[88:89]
	global_store_dwordx4 v[62:63], v[96:99], off
	v_add_f32_e32 v2, 1.0, v2
	v_rcp_f32_e32 v95, v2
	s_nop 0
	v_pk_mul_f32 v[92:93], v[94:95], v[92:93]
	s_nop 0
	v_pk_mul_f32 v[76:77], v[92:93], v[76:77]
	s_nop 0
	v_cvt_pk_bf16_f32 v92, v76, v77
	v_lshlrev_b32_e32 v76, 16, v137
	v_mul_f32_e32 v2, 0xbfb8aa3b, v76
	v_exp_f32_e32 v2, v2
	v_and_b32_e32 v77, 0xffff0000, v137
	v_add_f32_e32 v2, 1.0, v2
	v_rcp_f32_e32 v94, v2
	v_mul_f32_e32 v2, 0xbfb8aa3b, v77
	v_exp_f32_e32 v2, v2
	s_nop 0
	v_add_f32_e32 v2, 1.0, v2
	v_rcp_f32_e32 v95, v2
	s_nop 0
	v_pk_mul_f32 v[76:77], v[94:95], v[76:77]
	s_nop 0
	v_pk_mul_f32 v[76:77], v[76:77], v[80:81]
	s_nop 0
	v_cvt_pk_bf16_f32 v93, v76, v77
	v_lshlrev_b32_e32 v76, 16, v138
	v_mul_f32_e32 v2, 0xbfb8aa3b, v76
	v_exp_f32_e32 v2, v2
	v_and_b32_e32 v77, 0xffff0000, v138
	v_add_f32_e32 v2, 1.0, v2
;       #define SILU_(x) ((x)*__builtin_amdgcn_rcpf(1.f+__builtin_amdgcn_exp2f(-1.4426950408889634f*(x))))
; __device__ __forceinline__ unsigned pkbf(float lo, float hi) { const f32x2r v = {lo, hi}; return __builtin_bit_cast(unsigned, __builtin_convertvector(v, bf16x2r)); }
; #define LBAR() do { asm volatile("s_waitcnt lgkmcnt(0)" ::: "memory"); __builtin_amdgcn_s_barrier(); asm volatile("" ::: "memory"); } while (0)
; #define SILU_(x) ((x) * __builtin_amdgcn_rcpf(1.f + __builtin_amdgcn_exp2f(-1.4426950408889634f * (x))))
; __device__ __forceinline__ void out_unit(RLAS unsigned char* L, int b, int h, int c, const bf16_t* QR, bf16_t* PR, const bf16_t* KR, const bf16_t* VR, const bf16_t* GR, const bf16_t* ST, size_t stbatch, const float* gnw, float lgf, float lgb, OutRegs& PF, bool is_first, bool has_next, int nb, int nh ...
;     ...
;       for (int i = 0; i < 4; ++i) { const float rstd = rsqrtf(vq[i] * (1.f / 128.f) + EPS); const u32x4 gw = gwr[i];
;           const f32x4 a0 = o[i][0] * rstd * w0, a1 = o[i][1] * rstd * w1; u32x4 ow;
;     ...
;           const float g0 = __uint_as_float(gw.x << 16), g1 = __uint_as_float(gw.x & 0xffff0000u), g2 = __uint_as_float(gw.y << 16), g3 = __uint_as_float(gw.y & 0xffff0000u), g4 = __uint_as_float(gw.z << 16), g5 = __uint_as_float(gw.z & 0xffff0000u), g6 = __uint_as_float(gw.w << 16), g7 = __uint_as_float(gw.w & 0xffff0000u);
;           ow.x = pkbf(a0[0] * SILU_(g0), a0[1] * SILU_(g1)); ow.y = pkbf(a0[2] * SILU_(g2), a0[3] * SILU_(g3));
;           ow.z = pkbf(a1[0] * SILU_(g4), a1[1] * SILU_(g5)); ow.w = pkbf(a1[2] * SILU_(g6), a1[3] * SILU_(g7));
;     ...
;           *(u32x4*)(op + (size_t)(4 * i) * QRP) = ow; } }
;     LBAR();
	v_rcp_f32_e32 v80, v2
	v_mul_f32_e32 v2, 0xbfb8aa3b, v77
	v_exp_f32_e32 v2, v2
	s_nop 0
	v_add_f32_e32 v2, 1.0, v2
	v_rcp_f32_e32 v81, v2
	s_nop 0
	v_pk_mul_f32 v[76:77], v[80:81], v[76:77]
	s_nop 0
	v_pk_mul_f32 v[76:77], v[76:77], v[84:85]
	s_nop 0
	v_cvt_pk_bf16_f32 v94, v76, v77
	v_lshlrev_b32_e32 v76, 16, v139
	v_mul_f32_e32 v2, 0xbfb8aa3b, v76
	v_exp_f32_e32 v2, v2
	v_and_b32_e32 v77, 0xffff0000, v139
	v_add_f32_e32 v2, 1.0, v2
	v_rcp_f32_e32 v80, v2
	v_mul_f32_e32 v2, 0xbfb8aa3b, v77
	v_exp_f32_e32 v2, v2
	s_nop 0
	v_add_f32_e32 v2, 1.0, v2
	v_rcp_f32_e32 v81, v2
	s_nop 0
	v_pk_mul_f32 v[76:77], v[80:81], v[76:77]
	s_nop 0
	v_pk_mul_f32 v[76:77], v[76:77], v[88:89]
	s_nop 0
	v_cvt_pk_bf16_f32 v95, v76, v77
	v_add_co_u32_e32 v76, vcc, s7, v62
	s_nop 1
	v_addc_co_u32_e32 v77, vcc, 0, v63, vcc
	global_store_dwordx4 v[76:77], v[92:95], off
	v_lshlrev_b32_e32 v76, 16, v132
	v_mul_f32_e32 v2, 0xbfb8aa3b, v76
	v_exp_f32_e32 v2, v2
	v_and_b32_e32 v77, 0xffff0000, v132
	v_add_f32_e32 v2, 1.0, v2
	v_rcp_f32_e32 v80, v2
	v_mul_f32_e32 v2, 0xbfb8aa3b, v77
	v_exp_f32_e32 v2, v2
	s_nop 0
	v_add_f32_e32 v2, 1.0, v2
	v_rcp_f32_e32 v81, v2
	s_nop 0
	v_pk_mul_f32 v[76:77], v[80:81], v[76:77]
	v_lshlrev_b32_e32 v80, 16, v133
	v_mul_f32_e32 v2, 0xbfb8aa3b, v80
	v_exp_f32_e32 v2, v2
	v_and_b32_e32 v81, 0xffff0000, v133
	v_add_f32_e32 v2, 1.0, v2
	v_rcp_f32_e32 v84, v2
	v_mul_f32_e32 v2, 0xbfb8aa3b, v81
	v_exp_f32_e32 v2, v2
	s_nop 0
	v_add_f32_e32 v2, 1.0, v2
	v_rcp_f32_e32 v85, v2
	s_nop 0
	v_pk_mul_f32 v[80:81], v[84:85], v[80:81]
	v_lshlrev_b32_e32 v84, 16, v134
	v_mul_f32_e32 v2, 0xbfb8aa3b, v84
	v_exp_f32_e32 v2, v2
	v_and_b32_e32 v85, 0xffff0000, v134
	v_add_f32_e32 v2, 1.0, v2
	v_rcp_f32_e32 v88, v2
	v_mul_f32_e32 v2, 0xbfb8aa3b, v85
	v_exp_f32_e32 v2, v2
	s_nop 0
	v_add_f32_e32 v2, 1.0, v2
	v_rcp_f32_e32 v89, v2
	s_nop 0
	v_pk_mul_f32 v[84:85], v[88:89], v[84:85]
	v_lshlrev_b32_e32 v88, 16, v135
	v_mul_f32_e32 v2, 0xbfb8aa3b, v88
	v_exp_f32_e32 v2, v2
	v_and_b32_e32 v89, 0xffff0000, v135
	v_add_f32_e32 v2, 1.0, v2
	v_rcp_f32_e32 v92, v2
	v_mul_f32_e32 v2, 0xbfb8aa3b, v89
	v_exp_f32_e32 v2, v2
	s_nop 0
	v_add_f32_e32 v2, 1.0, v2
	v_rcp_f32_e32 v93, v2
	s_nop 0
	v_pk_mul_f32 v[88:89], v[92:93], v[88:89]
	v_mov_b32_e32 v92, v86
	v_mov_b32_e32 v93, v82
	v_mov_b32_e32 v82, v87
	v_pk_add_f32 v[82:83], v[92:93], v[82:83]
	s_nop 1
	v_mov_b32_dpp v87, v83 quad_perm:[1,0,3,2] row_mask:0xf bank_mask:0xf bound_ctrl:1
	v_mov_b32_dpp v86, v82 quad_perm:[1,0,3,2] row_mask:0xf bank_mask:0xf bound_ctrl:1
	v_pk_add_f32 v[82:83], v[82:83], v[86:87]
	s_nop 1
	v_mov_b32_dpp v87, v83 quad_perm:[2,3,0,1] row_mask:0xf bank_mask:0xf bound_ctrl:1
	v_mov_b32_dpp v86, v82 quad_perm:[2,3,0,1] row_mask:0xf bank_mask:0xf bound_ctrl:1
	v_pk_add_f32 v[82:83], v[82:83], v[86:87]
	s_nop 1
	v_mov_b32_dpp v87, v83 row_half_mirror row_mask:0xf bank_mask:0xf bound_ctrl:1
	v_mov_b32_dpp v86, v82 row_half_mirror row_mask:0xf bank_mask:0xf bound_ctrl:1
	v_pk_add_f32 v[82:83], v[82:83], v[86:87]
	s_nop 1
	v_mov_b32_dpp v87, v83 row_mirror row_mask:0xf bank_mask:0xf bound_ctrl:1
	v_mov_b32_dpp v86, v82 row_mirror row_mask:0xf bank_mask:0xf bound_ctrl:1
	v_pk_add_f32 v[82:83], v[82:83], v[86:87]
	s_nop 0
	v_pk_fma_f32 v[82:83], v[82:83], s[0:1], v[90:91] op_sel_hi:[1,0,0]
	s_mov_b64 s[0:1], 0
	v_mul_f32_e32 v2, 0x4b800000, v83
	v_cmp_gt_f32_e64 s[38:39], s35, v83
	v_cmp_gt_f32_e32 vcc, s35, v82
	s_nop 0
	v_cndmask_b32_e64 v2, v83, v2, s[38:39]
	v_rsq_f32_e32 v2, v2
	s_nop 0
	v_mul_f32_e32 v83, 0x45800000, v2
	v_cndmask_b32_e64 v2, v2, v83, s[38:39]
	v_pk_mul_f32 v[72:73], v[72:73], v[2:3] op_sel_hi:[1,0]
	v_pk_mul_f32 v[74:75], v[74:75], v[2:3] op_sel_hi:[1,0]
	v_pk_mul_f32 v[68:69], v[68:69], v[2:3] op_sel_hi:[1,0]
	v_pk_mul_f32 v[78:79], v[78:79], v[2:3] op_sel_hi:[1,0]
	v_mul_f32_e32 v2, 0x4b800000, v82
	v_pk_mul_f32 v[74:75], v[58:59], v[74:75]
	v_pk_mul_f32 v[72:73], v[56:57], v[72:73]
	v_pk_mul_f32 v[68:69], v[52:53], v[68:69]
	v_cndmask_b32_e32 v2, v82, v2, vcc
	v_pk_mul_f32 v[78:79], v[54:55], v[78:79]
	v_pk_mul_f32 v[72:73], v[76:77], v[72:73]
	v_pk_mul_f32 v[74:75], v[80:81], v[74:75]
	v_pk_mul_f32 v[68:69], v[84:85], v[68:69]
	v_rsq_f32_e32 v2, v2
	v_cvt_pk_bf16_f32 v72, v72, v73
	v_cvt_pk_bf16_f32 v73, v74, v75
	v_cvt_pk_bf16_f32 v74, v68, v69
	v_pk_mul_f32 v[68:69], v[88:89], v[78:79]
	s_nop 0
	v_cvt_pk_bf16_f32 v75, v68, v69
	v_add_co_u32_e64 v68, s[38:39], s6, v62
	s_nop 1
	v_addc_co_u32_e64 v69, s[38:39], 0, v63, s[38:39]
	global_store_dwordx4 v[68:69], v[72:75], off
	v_mul_f32_e32 v68, 0x45800000, v2
	v_cndmask_b32_e32 v2, v2, v68, vcc
	v_pk_mul_f32 v[64:65], v[64:65], v[2:3] op_sel_hi:[1,0]
	v_pk_mul_f32 v[60:61], v[60:61], v[2:3] op_sel_hi:[1,0]
	v_pk_mul_f32 v[56:57], v[56:57], v[64:65]
	v_pk_mul_f32 v[64:65], v[70:71], v[2:3] op_sel_hi:[1,0]
	v_pk_mul_f32 v[66:67], v[66:67], v[2:3] op_sel_hi:[1,0]
	v_pk_mul_f32 v[64:65], v[54:55], v[64:65]
	v_pk_mul_f32 v[54:55], v[52:53], v[60:61]
	v_lshlrev_b32_e32 v52, 16, v128
	v_mul_f32_e32 v2, 0xbfb8aa3b, v52
	v_exp_f32_e32 v2, v2
	v_and_b32_e32 v53, 0xffff0000, v128
	v_pk_mul_f32 v[58:59], v[58:59], v[66:67]
	v_add_f32_e32 v2, 1.0, v2
	v_rcp_f32_e32 v60, v2
	v_mul_f32_e32 v2, 0xbfb8aa3b, v53
	v_exp_f32_e32 v2, v2
	s_nop 0
	v_add_f32_e32 v2, 1.0, v2
	v_rcp_f32_e32 v61, v2
	s_nop 0
	v_pk_mul_f32 v[52:53], v[60:61], v[52:53]
	s_nop 0
	v_pk_mul_f32 v[52:53], v[52:53], v[56:57]
	v_lshlrev_b32_e32 v56, 16, v129
	v_mul_f32_e32 v2, 0xbfb8aa3b, v56
	v_exp_f32_e32 v2, v2
	v_and_b32_e32 v57, 0xffff0000, v129
	v_cvt_pk_bf16_f32 v52, v52, v53
	v_add_f32_e32 v2, 1.0, v2
	v_rcp_f32_e32 v60, v2
	v_mul_f32_e32 v2, 0xbfb8aa3b, v57
	v_exp_f32_e32 v2, v2
	s_nop 0
	v_add_f32_e32 v2, 1.0, v2
	v_rcp_f32_e32 v61, v2
	s_nop 0
	v_pk_mul_f32 v[56:57], v[60:61], v[56:57]
	s_nop 0
	v_pk_mul_f32 v[56:57], v[56:57], v[58:59]
	s_nop 0
	v_cvt_pk_bf16_f32 v53, v56, v57
	v_lshlrev_b32_e32 v56, 16, v130
	v_mul_f32_e32 v2, 0xbfb8aa3b, v56
	v_exp_f32_e32 v2, v2
	v_and_b32_e32 v57, 0xffff0000, v130
	v_add_f32_e32 v2, 1.0, v2
	v_rcp_f32_e32 v58, v2
	v_mul_f32_e32 v2, 0xbfb8aa3b, v57
	v_exp_f32_e32 v2, v2
	s_nop 0
	v_add_f32_e32 v2, 1.0, v2
	v_rcp_f32_e32 v59, v2
	s_nop 0
	v_pk_mul_f32 v[56:57], v[58:59], v[56:57]
	s_nop 0
	v_pk_mul_f32 v[54:55], v[56:57], v[54:55]
	v_lshlrev_b32_e32 v56, 16, v131
	v_mul_f32_e32 v2, 0xbfb8aa3b, v56
	v_exp_f32_e32 v2, v2
	v_and_b32_e32 v57, 0xffff0000, v131
	v_cvt_pk_bf16_f32 v54, v54, v55
	v_add_f32_e32 v2, 1.0, v2
	v_rcp_f32_e32 v58, v2
	v_mul_f32_e32 v2, 0xbfb8aa3b, v57
	v_exp_f32_e32 v2, v2
	s_nop 0
	v_add_f32_e32 v2, 1.0, v2
	v_rcp_f32_e32 v59, v2
	s_nop 0
	v_pk_mul_f32 v[56:57], v[58:59], v[56:57]
	s_nop 0
	v_pk_mul_f32 v[56:57], v[56:57], v[64:65]
	s_nop 0
	v_cvt_pk_bf16_f32 v55, v56, v57
	v_add_co_u32_e32 v56, vcc, 0x6000, v62
	s_nop 1
	v_addc_co_u32_e32 v57, vcc, 0, v63, vcc
	global_store_dwordx4 v[56:57], v[52:55], off
	s_waitcnt lgkmcnt(0)
	s_barrier

; __global__ void __launch_bounds__(NWAVES * 64, 2) mega_fwd(Args args) {
	.amdhsa_kernel _Z8mega_fwd4Args
		.amdhsa_group_segment_fixed_size 0
		.amdhsa_private_segment_fixed_size 0
		.amdhsa_kernarg_size 384
		.amdhsa_user_sgpr_count 2
		.amdhsa_user_sgpr_dispatch_ptr 0
		.amdhsa_user_sgpr_queue_ptr 0
		.amdhsa_user_sgpr_kernarg_segment_ptr 1
		.amdhsa_user_sgpr_dispatch_id 0
		.amdhsa_user_sgpr_kernarg_preload_length 0
		.amdhsa_user_sgpr_kernarg_preload_offset 0
		.amdhsa_user_sgpr_private_segment_size 0
		.amdhsa_uses_dynamic_stack 0
		.amdhsa_enable_private_segment 0
		.amdhsa_system_sgpr_workgroup_id_x 1
		.amdhsa_system_sgpr_workgroup_id_y 0
		.amdhsa_system_sgpr_workgroup_id_z 0
		.amdhsa_system_sgpr_workgroup_info 0
		.amdhsa_system_vgpr_workitem_id 0
		.amdhsa_next_free_vgpr 256
		.amdhsa_next_free_sgpr 102
		.amdhsa_accum_offset 256
		.amdhsa_reserve_vcc 1
		.amdhsa_float_round_mode_32 0
		.amdhsa_float_round_mode_16_64 0
		.amdhsa_float_denorm_mode_32 3
		.amdhsa_float_denorm_mode_16_64 3
		.amdhsa_dx10_clamp 1
		.amdhsa_ieee_mode 1
		.amdhsa_fp16_overflow 0
		.amdhsa_tg_split 0
		.amdhsa_exception_fp_ieee_invalid_op 0
		.amdhsa_exception_fp_denorm_src 0
		.amdhsa_exception_fp_ieee_div_zero 0
		.amdhsa_exception_fp_ieee_overflow 0
		.amdhsa_exception_fp_ieee_underflow 0
		.amdhsa_exception_fp_ieee_inexact 0
		.amdhsa_exception_int_div_zero 0
	.end_amdhsa_kernel

; __global__ void __launch_bounds__(NWAVES * 64, 2) mega_fwd(Args args) {
amdhsa.kernels:
  - .agpr_count:     0
    .args:
      - .offset:         0
        .size:           128
        .value_kind:     by_value
      - .offset:         128
        .size:           4
        .value_kind:     hidden_block_count_x
      - .offset:         132
        .size:           4
        .value_kind:     hidden_block_count_y
      - .offset:         136
        .size:           4
        .value_kind:     hidden_block_count_z
      - .offset:         140
        .size:           2
        .value_kind:     hidden_group_size_x
      - .offset:         142
        .size:           2
        .value_kind:     hidden_group_size_y
      - .offset:         144
        .size:           2
        .value_kind:     hidden_group_size_z
      - .offset:         146
        .size:           2
        .value_kind:     hidden_remainder_x
      - .offset:         148
        .size:           2
        .value_kind:     hidden_remainder_y
      - .offset:         150
        .size:           2
        .value_kind:     hidden_remainder_z
      - .offset:         168
        .size:           8
        .value_kind:     hidden_global_offset_x
      - .offset:         176
        .size:           8
        .value_kind:     hidden_global_offset_y
      - .offset:         184
        .size:           8
        .value_kind:     hidden_global_offset_z
      - .offset:         192
        .size:           2
        .value_kind:     hidden_grid_dims
      - .offset:         248
        .size:           4
        .value_kind:     hidden_dynamic_lds_size
    .group_segment_fixed_size: 0
    .kernarg_segment_align: 8
    .kernarg_segment_size: 384
    .language:       OpenCL C
    .language_version:
      - 2
      - 0
    .max_flat_workgroup_size: 512
    .name:           _Z8mega_fwd4Args
    .private_segment_fixed_size: 0
    .sgpr_count:     108
    .sgpr_spill_count: 234
    .symbol:         _Z8mega_fwd4Args.kd
    .uniform_work_group_size: 1
    .uses_dynamic_stack: false
    .vgpr_count:     256
    .vgpr_spill_count: 0
    .wavefront_size: 64
